# conv branch restructured: row-major pk_fma accumulation (16 independent token chains), LN partial sums reduced with DPP row ops instead of 192 ds_bpermute, normalize stage batched; plus v020 changes
# speedup vs baseline: 1.0129x; 1.0129x over previous
; __device__ __forceinline__ float sigmoid_fast(float x) { return __builtin_amdgcn_rcpf(1.0f + __builtin_amdgcn_exp2f(-1.4426950408889634f * x)); }
; #define LAS __attribute__((address_space(3)))
; __device__ __forceinline__ unsigned pk2(float lo, float hi) { return pg8::cvt_pk_bf16(lo, hi); }
; #define CBAR() do { LDS_WAIT(); asm volatile("" ::: "memory"); __builtin_amdgcn_s_barrier(); asm volatile("" ::: "memory"); } while (0)
; __device__ __forceinline__ void p3_conv(const Ptrs& P, LAS unsigned char* lds, int first, int stride, int tid, int wave, int lane) {
;     ...
;         CBAR();
; #pragma unroll
;         for (int t = 0; t < 16; ++t) {
;             const float mu = stat[t * 2], rs = stat[t * 2 + 1];
;             const float y0 = (a[t].x - mu) * rs * lg.x + lb.x, y1 = (a[t].y - mu) * rs * lg.y + lb.y;
;             *(LAS unsigned*)(lds + OT_OFF + t * 2048 + tid * 4) = pk2(y0 * pg8::sigmoid_fast(y0), y1 * pg8::sigmoid_fast(y1));
;         }
.LBB0_366:
	s_or_b64 exec, exec, s[20:21]
	s_waitcnt lgkmcnt(0)
	s_barrier
	s_andn2_b64 vcc, exec, s[18:19]
	s_mov_b32 s0, s87
	v_mov_b32_e32 v242, s36
	ds_read_b128 v[72:75], v242
	ds_read_b128 v[76:79], v242 offset:16
	ds_read_b128 v[80:83], v242 offset:32
	ds_read_b128 v[84:87], v242 offset:48
	ds_read_b128 v[88:91], v242 offset:64
	ds_read_b128 v[92:95], v242 offset:80
	ds_read_b128 v[96:99], v242 offset:96
	ds_read_b128 v[100:103], v242 offset:112
	v_add_u32_e32 v243, s68, v173
	s_waitcnt lgkmcnt(0)
	v_sub_f32_e32 v204, v204, v72
	v_sub_f32_e32 v205, v205, v72
	v_sub_f32_e32 v206, v206, v74
	v_sub_f32_e32 v207, v207, v74
	v_sub_f32_e32 v208, v208, v76
	v_sub_f32_e32 v209, v209, v76
	v_sub_f32_e32 v210, v210, v78
	v_sub_f32_e32 v211, v211, v78
	v_sub_f32_e32 v212, v212, v80
	v_sub_f32_e32 v213, v213, v80
	v_sub_f32_e32 v214, v214, v82
	v_sub_f32_e32 v215, v215, v82
	v_sub_f32_e32 v216, v216, v84
	v_sub_f32_e32 v217, v217, v84
	v_sub_f32_e32 v218, v218, v86
	v_sub_f32_e32 v219, v219, v86
	v_sub_f32_e32 v220, v220, v88
	v_sub_f32_e32 v221, v221, v88
	v_sub_f32_e32 v222, v222, v90
	v_sub_f32_e32 v223, v223, v90
	v_sub_f32_e32 v224, v224, v92
	v_sub_f32_e32 v225, v225, v92
	v_sub_f32_e32 v226, v226, v94
	v_sub_f32_e32 v227, v227, v94
	v_sub_f32_e32 v228, v228, v96
	v_sub_f32_e32 v229, v229, v96
	v_sub_f32_e32 v230, v230, v98
	v_sub_f32_e32 v231, v231, v98
	v_sub_f32_e32 v232, v232, v100
	v_sub_f32_e32 v233, v233, v100
	v_sub_f32_e32 v234, v234, v102
	v_sub_f32_e32 v235, v235, v102
	v_mul_f32_e32 v204, v204, v73
	v_mul_f32_e32 v205, v205, v73
	v_mul_f32_e32 v206, v206, v75
	v_mul_f32_e32 v207, v207, v75
	v_mul_f32_e32 v208, v208, v77
	v_mul_f32_e32 v209, v209, v77
	v_mul_f32_e32 v210, v210, v79
	v_mul_f32_e32 v211, v211, v79
	v_mul_f32_e32 v212, v212, v81
	v_mul_f32_e32 v213, v213, v81
	v_mul_f32_e32 v214, v214, v83
	v_mul_f32_e32 v215, v215, v83
	v_mul_f32_e32 v216, v216, v85
	v_mul_f32_e32 v217, v217, v85
	v_mul_f32_e32 v218, v218, v87
	v_mul_f32_e32 v219, v219, v87
	v_mul_f32_e32 v220, v220, v89
	v_mul_f32_e32 v221, v221, v89
	v_mul_f32_e32 v222, v222, v91
	v_mul_f32_e32 v223, v223, v91
	v_mul_f32_e32 v224, v224, v93
	v_mul_f32_e32 v225, v225, v93
	v_mul_f32_e32 v226, v226, v95
	v_mul_f32_e32 v227, v227, v95
	v_mul_f32_e32 v228, v228, v97
	v_mul_f32_e32 v229, v229, v97
	v_mul_f32_e32 v230, v230, v99
	v_mul_f32_e32 v231, v231, v99
	v_mul_f32_e32 v232, v232, v101
	v_mul_f32_e32 v233, v233, v101
	v_mul_f32_e32 v234, v234, v103
	v_mul_f32_e32 v235, v235, v103
	v_fma_f32 v204, v66, v204, v68
	v_fma_f32 v205, v67, v205, v69
	v_fma_f32 v206, v66, v206, v68
	v_fma_f32 v207, v67, v207, v69
	v_fma_f32 v208, v66, v208, v68
	v_fma_f32 v209, v67, v209, v69
	v_fma_f32 v210, v66, v210, v68
	v_fma_f32 v211, v67, v211, v69
	v_fma_f32 v212, v66, v212, v68
	v_fma_f32 v213, v67, v213, v69
	v_fma_f32 v214, v66, v214, v68
	v_fma_f32 v215, v67, v215, v69
	v_fma_f32 v216, v66, v216, v68
	v_fma_f32 v217, v67, v217, v69
	v_fma_f32 v218, v66, v218, v68
	v_fma_f32 v219, v67, v219, v69
	v_fma_f32 v220, v66, v220, v68
	v_fma_f32 v221, v67, v221, v69
	v_fma_f32 v222, v66, v222, v68
	v_fma_f32 v223, v67, v223, v69
	v_fma_f32 v224, v66, v224, v68
	v_fma_f32 v225, v67, v225, v69
	v_fma_f32 v226, v66, v226, v68
	v_fma_f32 v227, v67, v227, v69
	v_fma_f32 v228, v66, v228, v68
	v_fma_f32 v229, v67, v229, v69
	v_fma_f32 v230, v66, v230, v68
	v_fma_f32 v231, v67, v231, v69
	v_fma_f32 v232, v66, v232, v68
	v_fma_f32 v233, v67, v233, v69
	v_fma_f32 v234, v66, v234, v68
	v_fma_f32 v235, v67, v235, v69
	v_mul_f32_e32 v104, 0xbfb8aa3b, v204
	v_mul_f32_e32 v105, 0xbfb8aa3b, v205
	v_mul_f32_e32 v106, 0xbfb8aa3b, v206
	v_mul_f32_e32 v107, 0xbfb8aa3b, v207
	v_mul_f32_e32 v108, 0xbfb8aa3b, v208
	v_mul_f32_e32 v109, 0xbfb8aa3b, v209
	v_mul_f32_e32 v110, 0xbfb8aa3b, v210
	v_mul_f32_e32 v111, 0xbfb8aa3b, v211
	v_mul_f32_e32 v112, 0xbfb8aa3b, v212
	v_mul_f32_e32 v113, 0xbfb8aa3b, v213
	v_mul_f32_e32 v114, 0xbfb8aa3b, v214
	v_mul_f32_e32 v115, 0xbfb8aa3b, v215
	v_mul_f32_e32 v116, 0xbfb8aa3b, v216
	v_mul_f32_e32 v117, 0xbfb8aa3b, v217
	v_mul_f32_e32 v118, 0xbfb8aa3b, v218
	v_mul_f32_e32 v119, 0xbfb8aa3b, v219
	v_mul_f32_e32 v120, 0xbfb8aa3b, v220
	v_mul_f32_e32 v121, 0xbfb8aa3b, v221
	v_mul_f32_e32 v122, 0xbfb8aa3b, v222
	v_mul_f32_e32 v123, 0xbfb8aa3b, v223
	v_mul_f32_e32 v124, 0xbfb8aa3b, v224
	v_mul_f32_e32 v125, 0xbfb8aa3b, v225
	v_mul_f32_e32 v126, 0xbfb8aa3b, v226
	v_mul_f32_e32 v127, 0xbfb8aa3b, v227
	v_mul_f32_e32 v128, 0xbfb8aa3b, v228
	v_mul_f32_e32 v129, 0xbfb8aa3b, v229
	v_mul_f32_e32 v130, 0xbfb8aa3b, v230
	v_mul_f32_e32 v131, 0xbfb8aa3b, v231
	v_mul_f32_e32 v132, 0xbfb8aa3b, v232
	v_mul_f32_e32 v133, 0xbfb8aa3b, v233
	v_mul_f32_e32 v134, 0xbfb8aa3b, v234
	v_mul_f32_e32 v135, 0xbfb8aa3b, v235
	v_exp_f32_e32 v104, v104
	v_exp_f32_e32 v105, v105
	v_exp_f32_e32 v106, v106
	v_exp_f32_e32 v107, v107
	v_exp_f32_e32 v108, v108
	v_exp_f32_e32 v109, v109
	v_exp_f32_e32 v110, v110
	v_exp_f32_e32 v111, v111
	v_exp_f32_e32 v112, v112
	v_exp_f32_e32 v113, v113
	v_exp_f32_e32 v114, v114
	v_exp_f32_e32 v115, v115
	v_exp_f32_e32 v116, v116
	v_exp_f32_e32 v117, v117
	v_exp_f32_e32 v118, v118
	v_exp_f32_e32 v119, v119
	v_exp_f32_e32 v120, v120
	v_exp_f32_e32 v121, v121
	v_exp_f32_e32 v122, v122
	v_exp_f32_e32 v123, v123
	v_exp_f32_e32 v124, v124
	v_exp_f32_e32 v125, v125
	v_exp_f32_e32 v126, v126
; __device__ __forceinline__ float sigmoid_fast(float x) { return __builtin_amdgcn_rcpf(1.0f + __builtin_amdgcn_exp2f(-1.4426950408889634f * x)); }
; #define LAS __attribute__((address_space(3)))
; __device__ __forceinline__ unsigned pk2(float lo, float hi) { return pg8::cvt_pk_bf16(lo, hi); }
; #define CBAR() do { LDS_WAIT(); asm volatile("" ::: "memory"); __builtin_amdgcn_s_barrier(); asm volatile("" ::: "memory"); } while (0)
; __device__ __forceinline__ void p3_conv(const Ptrs& P, LAS unsigned char* lds, int first, int stride, int tid, int wave, int lane) {
;     ...
; #pragma unroll
;         for (int t = 0; t < 16; ++t) {
;             const float mu = stat[t * 2], rs = stat[t * 2 + 1];
;             const float y0 = (a[t].x - mu) * rs * lg.x + lb.x, y1 = (a[t].y - mu) * rs * lg.y + lb.y;
;             *(LAS unsigned*)(lds + OT_OFF + t * 2048 + tid * 4) = pk2(y0 * pg8::sigmoid_fast(y0), y1 * pg8::sigmoid_fast(y1));
;         }
;         CBAR();
; #pragma unroll
;         for (int k = 0; k < 4; ++k) { const int c = tid + 512 * k; const v4u v = *(const LAS v4u*)(lds + OT_OFF + c * 16);
;             *(v4u*)((char*)P.MIX + ((size_t)(row0 + (c >> 7)) * DM + ATT_W) * 2 + (size_t)(c & 127) * 16) = v; }
;         CBAR();
	v_exp_f32_e32 v127, v127
	v_exp_f32_e32 v128, v128
	v_exp_f32_e32 v129, v129
	v_exp_f32_e32 v130, v130
	v_exp_f32_e32 v131, v131
	v_exp_f32_e32 v132, v132
	v_exp_f32_e32 v133, v133
	v_exp_f32_e32 v134, v134
	v_exp_f32_e32 v135, v135
	v_add_f32_e32 v104, 1.0, v104
	v_add_f32_e32 v105, 1.0, v105
	v_add_f32_e32 v106, 1.0, v106
	v_add_f32_e32 v107, 1.0, v107
	v_add_f32_e32 v108, 1.0, v108
	v_add_f32_e32 v109, 1.0, v109
	v_add_f32_e32 v110, 1.0, v110
	v_add_f32_e32 v111, 1.0, v111
	v_add_f32_e32 v112, 1.0, v112
	v_add_f32_e32 v113, 1.0, v113
	v_add_f32_e32 v114, 1.0, v114
	v_add_f32_e32 v115, 1.0, v115
	v_add_f32_e32 v116, 1.0, v116
	v_add_f32_e32 v117, 1.0, v117
	v_add_f32_e32 v118, 1.0, v118
	v_add_f32_e32 v119, 1.0, v119
	v_add_f32_e32 v120, 1.0, v120
	v_add_f32_e32 v121, 1.0, v121
	v_add_f32_e32 v122, 1.0, v122
	v_add_f32_e32 v123, 1.0, v123
	v_add_f32_e32 v124, 1.0, v124
	v_add_f32_e32 v125, 1.0, v125
	v_add_f32_e32 v126, 1.0, v126
	v_add_f32_e32 v127, 1.0, v127
	v_add_f32_e32 v128, 1.0, v128
	v_add_f32_e32 v129, 1.0, v129
	v_add_f32_e32 v130, 1.0, v130
	v_add_f32_e32 v131, 1.0, v131
	v_add_f32_e32 v132, 1.0, v132
	v_add_f32_e32 v133, 1.0, v133
	v_add_f32_e32 v134, 1.0, v134
	v_add_f32_e32 v135, 1.0, v135
	v_rcp_f32_e32 v104, v104
	v_rcp_f32_e32 v105, v105
	v_rcp_f32_e32 v106, v106
	v_rcp_f32_e32 v107, v107
	v_rcp_f32_e32 v108, v108
	v_rcp_f32_e32 v109, v109
	v_rcp_f32_e32 v110, v110
	v_rcp_f32_e32 v111, v111
	v_rcp_f32_e32 v112, v112
	v_rcp_f32_e32 v113, v113
	v_rcp_f32_e32 v114, v114
	v_rcp_f32_e32 v115, v115
	v_rcp_f32_e32 v116, v116
	v_rcp_f32_e32 v117, v117
	v_rcp_f32_e32 v118, v118
	v_rcp_f32_e32 v119, v119
	v_rcp_f32_e32 v120, v120
	v_rcp_f32_e32 v121, v121
	v_rcp_f32_e32 v122, v122
	v_rcp_f32_e32 v123, v123
	v_rcp_f32_e32 v124, v124
	v_rcp_f32_e32 v125, v125
	v_rcp_f32_e32 v126, v126
	v_rcp_f32_e32 v127, v127
	v_rcp_f32_e32 v128, v128
	v_rcp_f32_e32 v129, v129
	v_rcp_f32_e32 v130, v130
	v_rcp_f32_e32 v131, v131
	v_rcp_f32_e32 v132, v132
	v_rcp_f32_e32 v133, v133
	v_rcp_f32_e32 v134, v134
	v_rcp_f32_e32 v135, v135
	v_mul_f32_e32 v204, v204, v104
	v_mul_f32_e32 v205, v205, v105
	v_mul_f32_e32 v206, v206, v106
	v_mul_f32_e32 v207, v207, v107
	v_mul_f32_e32 v208, v208, v108
	v_mul_f32_e32 v209, v209, v109
	v_mul_f32_e32 v210, v210, v110
	v_mul_f32_e32 v211, v211, v111
	v_mul_f32_e32 v212, v212, v112
	v_mul_f32_e32 v213, v213, v113
	v_mul_f32_e32 v214, v214, v114
	v_mul_f32_e32 v215, v215, v115
	v_mul_f32_e32 v216, v216, v116
	v_mul_f32_e32 v217, v217, v117
	v_mul_f32_e32 v218, v218, v118
	v_mul_f32_e32 v219, v219, v119
	v_mul_f32_e32 v220, v220, v120
	v_mul_f32_e32 v221, v221, v121
	v_mul_f32_e32 v222, v222, v122
	v_mul_f32_e32 v223, v223, v123
	v_mul_f32_e32 v224, v224, v124
	v_mul_f32_e32 v225, v225, v125
	v_mul_f32_e32 v226, v226, v126
	v_mul_f32_e32 v227, v227, v127
	v_mul_f32_e32 v228, v228, v128
	v_mul_f32_e32 v229, v229, v129
	v_mul_f32_e32 v230, v230, v130
	v_mul_f32_e32 v231, v231, v131
	v_mul_f32_e32 v232, v232, v132
	v_mul_f32_e32 v233, v233, v133
	v_mul_f32_e32 v234, v234, v134
	v_mul_f32_e32 v235, v235, v135
	v_cvt_pk_bf16_f32 v104, v204, v205
	v_cvt_pk_bf16_f32 v106, v206, v207
	v_cvt_pk_bf16_f32 v108, v208, v209
	v_cvt_pk_bf16_f32 v110, v210, v211
	v_cvt_pk_bf16_f32 v112, v212, v213
	v_cvt_pk_bf16_f32 v114, v214, v215
	v_cvt_pk_bf16_f32 v116, v216, v217
	v_cvt_pk_bf16_f32 v118, v218, v219
	v_cvt_pk_bf16_f32 v120, v220, v221
	v_cvt_pk_bf16_f32 v122, v222, v223
	v_cvt_pk_bf16_f32 v124, v224, v225
	v_cvt_pk_bf16_f32 v126, v226, v227
	v_cvt_pk_bf16_f32 v128, v228, v229
	v_cvt_pk_bf16_f32 v130, v230, v231
	v_cvt_pk_bf16_f32 v132, v232, v233
	v_cvt_pk_bf16_f32 v134, v234, v235
	ds_write_b32 v243, v104
	ds_write_b32 v243, v106 offset:2048
	ds_write_b32 v243, v108 offset:4096
	ds_write_b32 v243, v110 offset:6144
	ds_write_b32 v243, v112 offset:8192
	ds_write_b32 v243, v114 offset:10240
	ds_write_b32 v243, v116 offset:12288
	ds_write_b32 v243, v118 offset:14336
	ds_write_b32 v243, v120 offset:16384
	ds_write_b32 v243, v122 offset:18432
	ds_write_b32 v243, v124 offset:20480
	ds_write_b32 v243, v126 offset:22528
	ds_write_b32 v243, v128 offset:24576
	ds_write_b32 v243, v130 offset:26624
	ds_write_b32 v243, v132 offset:28672
	ds_write_b32 v243, v134 offset:30720
	s_waitcnt lgkmcnt(0)
	s_barrier
	v_add_u32_e32 v72, s68, v177
	ds_read_b128 v[72:75], v72
	v_or_b32_e32 v76, s88, v192
	v_ashrrev_i32_e32 v77, 31, v76
	v_lshlrev_b64 v[76:77], 12, v[76:77]
	v_lshl_add_u64 v[76:77], v[70:71], 0, v[76:77]
	s_waitcnt lgkmcnt(0)
	flat_store_dwordx4 v[76:77], v[72:75] offset:2048
	ds_read_b128 v[72:75], v197
	v_or_b32_e32 v76, s88, v193
	v_ashrrev_i32_e32 v77, 31, v76
	v_lshlrev_b64 v[76:77], 12, v[76:77]
	v_lshl_add_u64 v[76:77], v[70:71], 0, v[76:77]
	s_waitcnt lgkmcnt(0)
	flat_store_dwordx4 v[76:77], v[72:75] offset:2048
	ds_read_b128 v[72:75], v198
	v_or_b32_e32 v76, s88, v194
	v_ashrrev_i32_e32 v77, 31, v76
	v_lshlrev_b64 v[76:77], 12, v[76:77]
	v_lshl_add_u64 v[76:77], v[70:71], 0, v[76:77]
	s_waitcnt lgkmcnt(0)
	flat_store_dwordx4 v[76:77], v[72:75] offset:2048
	ds_read_b128 v[72:75], v199
	v_add_u32_e32 v76, s88, v195
	v_ashrrev_i32_e32 v77, 31, v76
	v_lshlrev_b64 v[76:77], 12, v[76:77]
	v_lshl_add_u64 v[76:77], v[70:71], 0, v[76:77]
	s_waitcnt lgkmcnt(0)
	flat_store_dwordx4 v[76:77], v[72:75] offset:2048
	s_waitcnt lgkmcnt(0)
	s_barrier
	s_cbranch_vccz .LBB0_406

; #define LAS __attribute__((address_space(3)))
; #define CBAR() do { LDS_WAIT(); asm volatile("" ::: "memory"); __builtin_amdgcn_s_barrier(); asm volatile("" ::: "memory"); } while (0)
; __device__ __forceinline__ void p3_conv(const Ptrs& P, LAS unsigned char* lds, int first, int stride, int tid, int wave, int lane) {
;     ...
;         unsigned uv[46];
; #pragma unroll
;         for (int r = 0; r < 46; ++r) { const int neg = (s0 - 30 + r) >> 31;
;             uv[r] = *(const LAS unsigned*)(lds + r * 2048 + tid * 4) & ~(unsigned)neg; }
;         CBAR();
;         if (item + stride < NITEMS) CONV_ISSUE(item + stride);
;         f32x2 a[16];
; #pragma unroll
;         for (int t = 0; t < 16; ++t) a[t] = cb;
; #pragma unroll
;         for (int r = 0; r < 46; ++r) {
;             const f32x2 u = (f32x2){bflo(uv[r]), bfhi(uv[r])};
; #pragma unroll
;             for (int t = 0; t < 16; ++t) { const int k = r - t; if (k >= 0 && k < CONV_W) a[t] += u * w[k]; }
;         }
.LBB0_372:
	s_lshl_b32 s88, s0, 4
	s_and_b32 s0, s88, 0x1ff0
	s_waitcnt lgkmcnt(0)
	s_cmp_gt_u32 s0, 16
	s_cbranch_scc1 .Lcv_nomask
	v_mov_b32_e32 v102, 0
	v_mov_b32_e32 v103, 0
	v_mov_b32_e32 v100, 0
	v_mov_b32_e32 v101, 0
	v_mov_b32_e32 v98, 0
	v_mov_b32_e32 v99, 0
	v_mov_b32_e32 v96, 0
	v_mov_b32_e32 v97, 0
	v_mov_b32_e32 v94, 0
	v_mov_b32_e32 v95, 0
	v_mov_b32_e32 v92, 0
	v_mov_b32_e32 v93, 0
	v_mov_b32_e32 v90, 0
	v_mov_b32_e32 v91, 0
	s_cmp_eq_u32 s0, 0
	s_cbranch_scc0 .Lcv_nomask
	v_mov_b32_e32 v88, 0
	v_mov_b32_e32 v89, 0
	v_mov_b32_e32 v86, 0
	v_mov_b32_e32 v87, 0
	v_mov_b32_e32 v84, 0
	v_mov_b32_e32 v85, 0
	v_mov_b32_e32 v82, 0
	v_mov_b32_e32 v83, 0
	v_mov_b32_e32 v80, 0
	v_mov_b32_e32 v81, 0
	v_mov_b32_e32 v78, 0
	v_mov_b32_e32 v79, 0
	v_mov_b32_e32 v76, 0
	v_mov_b32_e32 v77, 0
	v_mov_b32_e32 v72, 0
	v_mov_b32_e32 v73, 0
.Lcv_nomask:
	v_lshlrev_b32_e32 v236, 16, v102
	v_and_b32_e32 v237, 0xffff0000, v102
	v_pk_fma_f32 v[204:205], v[2:3], v[236:237], v[64:65]
	v_lshlrev_b32_e32 v238, 16, v103
	v_and_b32_e32 v239, 0xffff0000, v103
	v_pk_fma_f32 v[204:205], v[4:5], v[238:239], v[204:205]
	v_pk_fma_f32 v[206:207], v[2:3], v[238:239], v[64:65]
	v_lshlrev_b32_e32 v240, 16, v100
	v_and_b32_e32 v241, 0xffff0000, v100
	v_pk_fma_f32 v[204:205], v[6:7], v[240:241], v[204:205]
	v_pk_fma_f32 v[206:207], v[4:5], v[240:241], v[206:207]
	v_pk_fma_f32 v[208:209], v[2:3], v[240:241], v[64:65]
	v_lshlrev_b32_e32 v236, 16, v101
	v_and_b32_e32 v237, 0xffff0000, v101
	v_pk_fma_f32 v[204:205], v[8:9], v[236:237], v[204:205]
	v_pk_fma_f32 v[206:207], v[6:7], v[236:237], v[206:207]
	v_pk_fma_f32 v[208:209], v[4:5], v[236:237], v[208:209]
	v_pk_fma_f32 v[210:211], v[2:3], v[236:237], v[64:65]
	v_lshlrev_b32_e32 v238, 16, v98
	v_and_b32_e32 v239, 0xffff0000, v98
	v_pk_fma_f32 v[204:205], v[10:11], v[238:239], v[204:205]
	v_pk_fma_f32 v[206:207], v[8:9], v[238:239], v[206:207]
	v_pk_fma_f32 v[208:209], v[6:7], v[238:239], v[208:209]
	v_pk_fma_f32 v[210:211], v[4:5], v[238:239], v[210:211]
	v_pk_fma_f32 v[212:213], v[2:3], v[238:239], v[64:65]
	v_lshlrev_b32_e32 v240, 16, v99
	v_and_b32_e32 v241, 0xffff0000, v99
	v_pk_fma_f32 v[204:205], v[12:13], v[240:241], v[204:205]
	v_pk_fma_f32 v[206:207], v[10:11], v[240:241], v[206:207]
	v_pk_fma_f32 v[208:209], v[8:9], v[240:241], v[208:209]
	v_pk_fma_f32 v[210:211], v[6:7], v[240:241], v[210:211]
	v_pk_fma_f32 v[212:213], v[4:5], v[240:241], v[212:213]
	v_pk_fma_f32 v[214:215], v[2:3], v[240:241], v[64:65]
	v_lshlrev_b32_e32 v236, 16, v96
	v_and_b32_e32 v237, 0xffff0000, v96
	v_pk_fma_f32 v[204:205], v[14:15], v[236:237], v[204:205]
	v_pk_fma_f32 v[206:207], v[12:13], v[236:237], v[206:207]
	v_pk_fma_f32 v[208:209], v[10:11], v[236:237], v[208:209]
	v_pk_fma_f32 v[210:211], v[8:9], v[236:237], v[210:211]
	v_pk_fma_f32 v[212:213], v[6:7], v[236:237], v[212:213]
	v_pk_fma_f32 v[214:215], v[4:5], v[236:237], v[214:215]
	v_pk_fma_f32 v[216:217], v[2:3], v[236:237], v[64:65]
	v_lshlrev_b32_e32 v238, 16, v97
	v_and_b32_e32 v239, 0xffff0000, v97
	v_pk_fma_f32 v[204:205], v[16:17], v[238:239], v[204:205]
	v_pk_fma_f32 v[206:207], v[14:15], v[238:239], v[206:207]
	v_pk_fma_f32 v[208:209], v[12:13], v[238:239], v[208:209]
	v_pk_fma_f32 v[210:211], v[10:11], v[238:239], v[210:211]
	v_pk_fma_f32 v[212:213], v[8:9], v[238:239], v[212:213]
	v_pk_fma_f32 v[214:215], v[6:7], v[238:239], v[214:215]
	v_pk_fma_f32 v[216:217], v[4:5], v[238:239], v[216:217]
	v_pk_fma_f32 v[218:219], v[2:3], v[238:239], v[64:65]
	v_lshlrev_b32_e32 v240, 16, v94
	v_and_b32_e32 v241, 0xffff0000, v94
	v_pk_fma_f32 v[204:205], v[18:19], v[240:241], v[204:205]
	v_pk_fma_f32 v[206:207], v[16:17], v[240:241], v[206:207]
	v_pk_fma_f32 v[208:209], v[14:15], v[240:241], v[208:209]
	v_pk_fma_f32 v[210:211], v[12:13], v[240:241], v[210:211]
	v_pk_fma_f32 v[212:213], v[10:11], v[240:241], v[212:213]
	v_pk_fma_f32 v[214:215], v[8:9], v[240:241], v[214:215]
	v_pk_fma_f32 v[216:217], v[6:7], v[240:241], v[216:217]
	v_pk_fma_f32 v[218:219], v[4:5], v[240:241], v[218:219]
	v_pk_fma_f32 v[220:221], v[2:3], v[240:241], v[64:65]
	v_lshlrev_b32_e32 v236, 16, v95
	v_and_b32_e32 v237, 0xffff0000, v95
	v_pk_fma_f32 v[204:205], v[20:21], v[236:237], v[204:205]
	v_pk_fma_f32 v[206:207], v[18:19], v[236:237], v[206:207]
	v_pk_fma_f32 v[208:209], v[16:17], v[236:237], v[208:209]
	v_pk_fma_f32 v[210:211], v[14:15], v[236:237], v[210:211]
	v_pk_fma_f32 v[212:213], v[12:13], v[236:237], v[212:213]
	v_pk_fma_f32 v[214:215], v[10:11], v[236:237], v[214:215]
	v_pk_fma_f32 v[216:217], v[8:9], v[236:237], v[216:217]
	v_pk_fma_f32 v[218:219], v[6:7], v[236:237], v[218:219]
	v_pk_fma_f32 v[220:221], v[4:5], v[236:237], v[220:221]
	v_pk_fma_f32 v[222:223], v[2:3], v[236:237], v[64:65]
	v_lshlrev_b32_e32 v238, 16, v92
	v_and_b32_e32 v239, 0xffff0000, v92
	v_pk_fma_f32 v[204:205], v[22:23], v[238:239], v[204:205]
	v_pk_fma_f32 v[206:207], v[20:21], v[238:239], v[206:207]
	v_pk_fma_f32 v[208:209], v[18:19], v[238:239], v[208:209]
	v_pk_fma_f32 v[210:211], v[16:17], v[238:239], v[210:211]
	v_pk_fma_f32 v[212:213], v[14:15], v[238:239], v[212:213]
	v_pk_fma_f32 v[214:215], v[12:13], v[238:239], v[214:215]
	v_pk_fma_f32 v[216:217], v[10:11], v[238:239], v[216:217]
	v_pk_fma_f32 v[218:219], v[8:9], v[238:239], v[218:219]
	v_pk_fma_f32 v[220:221], v[6:7], v[238:239], v[220:221]
	v_pk_fma_f32 v[222:223], v[4:5], v[238:239], v[222:223]
	v_pk_fma_f32 v[224:225], v[2:3], v[238:239], v[64:65]
	v_lshlrev_b32_e32 v240, 16, v93
	v_and_b32_e32 v241, 0xffff0000, v93
	v_pk_fma_f32 v[204:205], v[24:25], v[240:241], v[204:205]
	v_pk_fma_f32 v[206:207], v[22:23], v[240:241], v[206:207]
; __device__ __forceinline__ void p3_conv(const Ptrs& P, LAS unsigned char* lds, int first, int stride, int tid, int wave, int lane) {
;     ...
;         f32x2 a[16];
; #pragma unroll
;         for (int t = 0; t < 16; ++t) a[t] = cb;
; #pragma unroll
;         for (int r = 0; r < 46; ++r) {
;             const f32x2 u = (f32x2){bflo(uv[r]), bfhi(uv[r])};
; #pragma unroll
;             for (int t = 0; t < 16; ++t) { const int k = r - t; if (k >= 0 && k < CONV_W) a[t] += u * w[k]; }
;         }
	v_pk_fma_f32 v[208:209], v[20:21], v[240:241], v[208:209]
	v_pk_fma_f32 v[210:211], v[18:19], v[240:241], v[210:211]
	v_pk_fma_f32 v[212:213], v[16:17], v[240:241], v[212:213]
	v_pk_fma_f32 v[214:215], v[14:15], v[240:241], v[214:215]
	v_pk_fma_f32 v[216:217], v[12:13], v[240:241], v[216:217]
	v_pk_fma_f32 v[218:219], v[10:11], v[240:241], v[218:219]
	v_pk_fma_f32 v[220:221], v[8:9], v[240:241], v[220:221]
	v_pk_fma_f32 v[222:223], v[6:7], v[240:241], v[222:223]
	v_pk_fma_f32 v[224:225], v[4:5], v[240:241], v[224:225]
	v_pk_fma_f32 v[226:227], v[2:3], v[240:241], v[64:65]
	v_lshlrev_b32_e32 v236, 16, v90
	v_and_b32_e32 v237, 0xffff0000, v90
	v_pk_fma_f32 v[204:205], v[26:27], v[236:237], v[204:205]
	v_pk_fma_f32 v[206:207], v[24:25], v[236:237], v[206:207]
	v_pk_fma_f32 v[208:209], v[22:23], v[236:237], v[208:209]
	v_pk_fma_f32 v[210:211], v[20:21], v[236:237], v[210:211]
	v_pk_fma_f32 v[212:213], v[18:19], v[236:237], v[212:213]
	v_pk_fma_f32 v[214:215], v[16:17], v[236:237], v[214:215]
	v_pk_fma_f32 v[216:217], v[14:15], v[236:237], v[216:217]
	v_pk_fma_f32 v[218:219], v[12:13], v[236:237], v[218:219]
	v_pk_fma_f32 v[220:221], v[10:11], v[236:237], v[220:221]
	v_pk_fma_f32 v[222:223], v[8:9], v[236:237], v[222:223]
	v_pk_fma_f32 v[224:225], v[6:7], v[236:237], v[224:225]
	v_pk_fma_f32 v[226:227], v[4:5], v[236:237], v[226:227]
	v_pk_fma_f32 v[228:229], v[2:3], v[236:237], v[64:65]
	v_lshlrev_b32_e32 v238, 16, v91
	v_and_b32_e32 v239, 0xffff0000, v91
	v_pk_fma_f32 v[204:205], v[28:29], v[238:239], v[204:205]
	v_pk_fma_f32 v[206:207], v[26:27], v[238:239], v[206:207]
	v_pk_fma_f32 v[208:209], v[24:25], v[238:239], v[208:209]
	v_pk_fma_f32 v[210:211], v[22:23], v[238:239], v[210:211]
	v_pk_fma_f32 v[212:213], v[20:21], v[238:239], v[212:213]
	v_pk_fma_f32 v[214:215], v[18:19], v[238:239], v[214:215]
	v_pk_fma_f32 v[216:217], v[16:17], v[238:239], v[216:217]
	v_pk_fma_f32 v[218:219], v[14:15], v[238:239], v[218:219]
	v_pk_fma_f32 v[220:221], v[12:13], v[238:239], v[220:221]
	v_pk_fma_f32 v[222:223], v[10:11], v[238:239], v[222:223]
	v_pk_fma_f32 v[224:225], v[8:9], v[238:239], v[224:225]
	v_pk_fma_f32 v[226:227], v[6:7], v[238:239], v[226:227]
	v_pk_fma_f32 v[228:229], v[4:5], v[238:239], v[228:229]
	v_pk_fma_f32 v[230:231], v[2:3], v[238:239], v[64:65]
	v_lshlrev_b32_e32 v240, 16, v88
	v_and_b32_e32 v241, 0xffff0000, v88
	v_pk_fma_f32 v[204:205], v[30:31], v[240:241], v[204:205]
	v_pk_fma_f32 v[206:207], v[28:29], v[240:241], v[206:207]
	v_pk_fma_f32 v[208:209], v[26:27], v[240:241], v[208:209]
	v_pk_fma_f32 v[210:211], v[24:25], v[240:241], v[210:211]
	v_pk_fma_f32 v[212:213], v[22:23], v[240:241], v[212:213]
	v_pk_fma_f32 v[214:215], v[20:21], v[240:241], v[214:215]
	v_pk_fma_f32 v[216:217], v[18:19], v[240:241], v[216:217]
	v_pk_fma_f32 v[218:219], v[16:17], v[240:241], v[218:219]
	v_pk_fma_f32 v[220:221], v[14:15], v[240:241], v[220:221]
	v_pk_fma_f32 v[222:223], v[12:13], v[240:241], v[222:223]
	v_pk_fma_f32 v[224:225], v[10:11], v[240:241], v[224:225]
	v_pk_fma_f32 v[226:227], v[8:9], v[240:241], v[226:227]
	v_pk_fma_f32 v[228:229], v[6:7], v[240:241], v[228:229]
	v_pk_fma_f32 v[230:231], v[4:5], v[240:241], v[230:231]
	v_pk_fma_f32 v[232:233], v[2:3], v[240:241], v[64:65]
	v_lshlrev_b32_e32 v236, 16, v89
	v_and_b32_e32 v237, 0xffff0000, v89
	v_pk_fma_f32 v[204:205], v[32:33], v[236:237], v[204:205]
	v_pk_fma_f32 v[206:207], v[30:31], v[236:237], v[206:207]
	v_pk_fma_f32 v[208:209], v[28:29], v[236:237], v[208:209]
	v_pk_fma_f32 v[210:211], v[26:27], v[236:237], v[210:211]
	v_pk_fma_f32 v[212:213], v[24:25], v[236:237], v[212:213]
	v_pk_fma_f32 v[214:215], v[22:23], v[236:237], v[214:215]
	v_pk_fma_f32 v[216:217], v[20:21], v[236:237], v[216:217]
	v_pk_fma_f32 v[218:219], v[18:19], v[236:237], v[218:219]
	v_pk_fma_f32 v[220:221], v[16:17], v[236:237], v[220:221]
	v_pk_fma_f32 v[222:223], v[14:15], v[236:237], v[222:223]
	v_pk_fma_f32 v[224:225], v[12:13], v[236:237], v[224:225]
	v_pk_fma_f32 v[226:227], v[10:11], v[236:237], v[226:227]
	v_pk_fma_f32 v[228:229], v[8:9], v[236:237], v[228:229]
	v_pk_fma_f32 v[230:231], v[6:7], v[236:237], v[230:231]
	v_pk_fma_f32 v[232:233], v[4:5], v[236:237], v[232:233]
	v_pk_fma_f32 v[234:235], v[2:3], v[236:237], v[64:65]
	v_lshlrev_b32_e32 v238, 16, v86
	v_and_b32_e32 v239, 0xffff0000, v86
	v_pk_fma_f32 v[204:205], v[34:35], v[238:239], v[204:205]
	v_pk_fma_f32 v[206:207], v[32:33], v[238:239], v[206:207]
	v_pk_fma_f32 v[208:209], v[30:31], v[238:239], v[208:209]
	v_pk_fma_f32 v[210:211], v[28:29], v[238:239], v[210:211]
	v_pk_fma_f32 v[212:213], v[26:27], v[238:239], v[212:213]
	v_pk_fma_f32 v[214:215], v[24:25], v[238:239], v[214:215]
	v_pk_fma_f32 v[216:217], v[22:23], v[238:239], v[216:217]
	v_pk_fma_f32 v[218:219], v[20:21], v[238:239], v[218:219]
	v_pk_fma_f32 v[220:221], v[18:19], v[238:239], v[220:221]
	v_pk_fma_f32 v[222:223], v[16:17], v[238:239], v[222:223]
	v_pk_fma_f32 v[224:225], v[14:15], v[238:239], v[224:225]
	v_pk_fma_f32 v[226:227], v[12:13], v[238:239], v[226:227]
	v_pk_fma_f32 v[228:229], v[10:11], v[238:239], v[228:229]
	v_pk_fma_f32 v[230:231], v[8:9], v[238:239], v[230:231]
	v_pk_fma_f32 v[232:233], v[6:7], v[238:239], v[232:233]
	v_pk_fma_f32 v[234:235], v[4:5], v[238:239], v[234:235]
	v_lshlrev_b32_e32 v240, 16, v87
	v_and_b32_e32 v241, 0xffff0000, v87
	v_pk_fma_f32 v[204:205], v[36:37], v[240:241], v[204:205]
	v_pk_fma_f32 v[206:207], v[34:35], v[240:241], v[206:207]
	v_pk_fma_f32 v[208:209], v[32:33], v[240:241], v[208:209]
	v_pk_fma_f32 v[210:211], v[30:31], v[240:241], v[210:211]
	v_pk_fma_f32 v[212:213], v[28:29], v[240:241], v[212:213]
; __device__ __forceinline__ void p3_conv(const Ptrs& P, LAS unsigned char* lds, int first, int stride, int tid, int wave, int lane) {
;     ...
;         f32x2 a[16];
; #pragma unroll
;         for (int t = 0; t < 16; ++t) a[t] = cb;
; #pragma unroll
;         for (int r = 0; r < 46; ++r) {
;             const f32x2 u = (f32x2){bflo(uv[r]), bfhi(uv[r])};
; #pragma unroll
;             for (int t = 0; t < 16; ++t) { const int k = r - t; if (k >= 0 && k < CONV_W) a[t] += u * w[k]; }
;         }
	v_pk_fma_f32 v[214:215], v[26:27], v[240:241], v[214:215]
	v_pk_fma_f32 v[216:217], v[24:25], v[240:241], v[216:217]
	v_pk_fma_f32 v[218:219], v[22:23], v[240:241], v[218:219]
	v_pk_fma_f32 v[220:221], v[20:21], v[240:241], v[220:221]
	v_pk_fma_f32 v[222:223], v[18:19], v[240:241], v[222:223]
	v_pk_fma_f32 v[224:225], v[16:17], v[240:241], v[224:225]
	v_pk_fma_f32 v[226:227], v[14:15], v[240:241], v[226:227]
	v_pk_fma_f32 v[228:229], v[12:13], v[240:241], v[228:229]
	v_pk_fma_f32 v[230:231], v[10:11], v[240:241], v[230:231]
	v_pk_fma_f32 v[232:233], v[8:9], v[240:241], v[232:233]
	v_pk_fma_f32 v[234:235], v[6:7], v[240:241], v[234:235]
	v_lshlrev_b32_e32 v236, 16, v84
	v_and_b32_e32 v237, 0xffff0000, v84
	v_pk_fma_f32 v[204:205], v[38:39], v[236:237], v[204:205]
	v_pk_fma_f32 v[206:207], v[36:37], v[236:237], v[206:207]
	v_pk_fma_f32 v[208:209], v[34:35], v[236:237], v[208:209]
	v_pk_fma_f32 v[210:211], v[32:33], v[236:237], v[210:211]
	v_pk_fma_f32 v[212:213], v[30:31], v[236:237], v[212:213]
	v_pk_fma_f32 v[214:215], v[28:29], v[236:237], v[214:215]
	v_pk_fma_f32 v[216:217], v[26:27], v[236:237], v[216:217]
	v_pk_fma_f32 v[218:219], v[24:25], v[236:237], v[218:219]
	v_pk_fma_f32 v[220:221], v[22:23], v[236:237], v[220:221]
	v_pk_fma_f32 v[222:223], v[20:21], v[236:237], v[222:223]
	v_pk_fma_f32 v[224:225], v[18:19], v[236:237], v[224:225]
	v_pk_fma_f32 v[226:227], v[16:17], v[236:237], v[226:227]
	v_pk_fma_f32 v[228:229], v[14:15], v[236:237], v[228:229]
	v_pk_fma_f32 v[230:231], v[12:13], v[236:237], v[230:231]
	v_pk_fma_f32 v[232:233], v[10:11], v[236:237], v[232:233]
	v_pk_fma_f32 v[234:235], v[8:9], v[236:237], v[234:235]
	v_lshlrev_b32_e32 v238, 16, v85
	v_and_b32_e32 v239, 0xffff0000, v85
	v_pk_fma_f32 v[204:205], v[40:41], v[238:239], v[204:205]
	v_pk_fma_f32 v[206:207], v[38:39], v[238:239], v[206:207]
	v_pk_fma_f32 v[208:209], v[36:37], v[238:239], v[208:209]
	v_pk_fma_f32 v[210:211], v[34:35], v[238:239], v[210:211]
	v_pk_fma_f32 v[212:213], v[32:33], v[238:239], v[212:213]
	v_pk_fma_f32 v[214:215], v[30:31], v[238:239], v[214:215]
	v_pk_fma_f32 v[216:217], v[28:29], v[238:239], v[216:217]
	v_pk_fma_f32 v[218:219], v[26:27], v[238:239], v[218:219]
	v_pk_fma_f32 v[220:221], v[24:25], v[238:239], v[220:221]
	v_pk_fma_f32 v[222:223], v[22:23], v[238:239], v[222:223]
	v_pk_fma_f32 v[224:225], v[20:21], v[238:239], v[224:225]
	v_pk_fma_f32 v[226:227], v[18:19], v[238:239], v[226:227]
	v_pk_fma_f32 v[228:229], v[16:17], v[238:239], v[228:229]
	v_pk_fma_f32 v[230:231], v[14:15], v[238:239], v[230:231]
	v_pk_fma_f32 v[232:233], v[12:13], v[238:239], v[232:233]
	v_pk_fma_f32 v[234:235], v[10:11], v[238:239], v[234:235]
	v_lshlrev_b32_e32 v240, 16, v82
	v_and_b32_e32 v241, 0xffff0000, v82
	v_pk_fma_f32 v[204:205], v[42:43], v[240:241], v[204:205]
	v_pk_fma_f32 v[206:207], v[40:41], v[240:241], v[206:207]
	v_pk_fma_f32 v[208:209], v[38:39], v[240:241], v[208:209]
	v_pk_fma_f32 v[210:211], v[36:37], v[240:241], v[210:211]
	v_pk_fma_f32 v[212:213], v[34:35], v[240:241], v[212:213]
	v_pk_fma_f32 v[214:215], v[32:33], v[240:241], v[214:215]
	v_pk_fma_f32 v[216:217], v[30:31], v[240:241], v[216:217]
	v_pk_fma_f32 v[218:219], v[28:29], v[240:241], v[218:219]
	v_pk_fma_f32 v[220:221], v[26:27], v[240:241], v[220:221]
	v_pk_fma_f32 v[222:223], v[24:25], v[240:241], v[222:223]
	v_pk_fma_f32 v[224:225], v[22:23], v[240:241], v[224:225]
	v_pk_fma_f32 v[226:227], v[20:21], v[240:241], v[226:227]
	v_pk_fma_f32 v[228:229], v[18:19], v[240:241], v[228:229]
	v_pk_fma_f32 v[230:231], v[16:17], v[240:241], v[230:231]
	v_pk_fma_f32 v[232:233], v[14:15], v[240:241], v[232:233]
	v_pk_fma_f32 v[234:235], v[12:13], v[240:241], v[234:235]
	v_lshlrev_b32_e32 v236, 16, v83
	v_and_b32_e32 v237, 0xffff0000, v83
	v_pk_fma_f32 v[204:205], v[44:45], v[236:237], v[204:205]
	v_pk_fma_f32 v[206:207], v[42:43], v[236:237], v[206:207]
	v_pk_fma_f32 v[208:209], v[40:41], v[236:237], v[208:209]
	v_pk_fma_f32 v[210:211], v[38:39], v[236:237], v[210:211]
	v_pk_fma_f32 v[212:213], v[36:37], v[236:237], v[212:213]
	v_pk_fma_f32 v[214:215], v[34:35], v[236:237], v[214:215]
	v_pk_fma_f32 v[216:217], v[32:33], v[236:237], v[216:217]
	v_pk_fma_f32 v[218:219], v[30:31], v[236:237], v[218:219]
	v_pk_fma_f32 v[220:221], v[28:29], v[236:237], v[220:221]
	v_pk_fma_f32 v[222:223], v[26:27], v[236:237], v[222:223]
	v_pk_fma_f32 v[224:225], v[24:25], v[236:237], v[224:225]
	v_pk_fma_f32 v[226:227], v[22:23], v[236:237], v[226:227]
	v_pk_fma_f32 v[228:229], v[20:21], v[236:237], v[228:229]
	v_pk_fma_f32 v[230:231], v[18:19], v[236:237], v[230:231]
	v_pk_fma_f32 v[232:233], v[16:17], v[236:237], v[232:233]
	v_pk_fma_f32 v[234:235], v[14:15], v[236:237], v[234:235]
	v_lshlrev_b32_e32 v238, 16, v80
	v_and_b32_e32 v239, 0xffff0000, v80
	v_pk_fma_f32 v[204:205], v[46:47], v[238:239], v[204:205]
	v_pk_fma_f32 v[206:207], v[44:45], v[238:239], v[206:207]
	v_pk_fma_f32 v[208:209], v[42:43], v[238:239], v[208:209]
	v_pk_fma_f32 v[210:211], v[40:41], v[238:239], v[210:211]
	v_pk_fma_f32 v[212:213], v[38:39], v[238:239], v[212:213]
	v_pk_fma_f32 v[214:215], v[36:37], v[238:239], v[214:215]
	v_pk_fma_f32 v[216:217], v[34:35], v[238:239], v[216:217]
	v_pk_fma_f32 v[218:219], v[32:33], v[238:239], v[218:219]
	v_pk_fma_f32 v[220:221], v[30:31], v[238:239], v[220:221]
	v_pk_fma_f32 v[222:223], v[28:29], v[238:239], v[222:223]
	v_pk_fma_f32 v[224:225], v[26:27], v[238:239], v[224:225]
	v_pk_fma_f32 v[226:227], v[24:25], v[238:239], v[226:227]
	v_pk_fma_f32 v[228:229], v[22:23], v[238:239], v[228:229]
	v_pk_fma_f32 v[230:231], v[20:21], v[238:239], v[230:231]
	v_pk_fma_f32 v[232:233], v[18:19], v[238:239], v[232:233]
; __device__ __forceinline__ void p3_conv(const Ptrs& P, LAS unsigned char* lds, int first, int stride, int tid, int wave, int lane) {
;     ...
;         f32x2 a[16];
; #pragma unroll
;         for (int t = 0; t < 16; ++t) a[t] = cb;
; #pragma unroll
;         for (int r = 0; r < 46; ++r) {
;             const f32x2 u = (f32x2){bflo(uv[r]), bfhi(uv[r])};
; #pragma unroll
;             for (int t = 0; t < 16; ++t) { const int k = r - t; if (k >= 0 && k < CONV_W) a[t] += u * w[k]; }
;         }
	v_pk_fma_f32 v[234:235], v[16:17], v[238:239], v[234:235]
	v_lshlrev_b32_e32 v240, 16, v81
	v_and_b32_e32 v241, 0xffff0000, v81
	v_pk_fma_f32 v[204:205], v[48:49], v[240:241], v[204:205]
	v_pk_fma_f32 v[206:207], v[46:47], v[240:241], v[206:207]
	v_pk_fma_f32 v[208:209], v[44:45], v[240:241], v[208:209]
	v_pk_fma_f32 v[210:211], v[42:43], v[240:241], v[210:211]
	v_pk_fma_f32 v[212:213], v[40:41], v[240:241], v[212:213]
	v_pk_fma_f32 v[214:215], v[38:39], v[240:241], v[214:215]
	v_pk_fma_f32 v[216:217], v[36:37], v[240:241], v[216:217]
	v_pk_fma_f32 v[218:219], v[34:35], v[240:241], v[218:219]
	v_pk_fma_f32 v[220:221], v[32:33], v[240:241], v[220:221]
	v_pk_fma_f32 v[222:223], v[30:31], v[240:241], v[222:223]
	v_pk_fma_f32 v[224:225], v[28:29], v[240:241], v[224:225]
	v_pk_fma_f32 v[226:227], v[26:27], v[240:241], v[226:227]
	v_pk_fma_f32 v[228:229], v[24:25], v[240:241], v[228:229]
	v_pk_fma_f32 v[230:231], v[22:23], v[240:241], v[230:231]
	v_pk_fma_f32 v[232:233], v[20:21], v[240:241], v[232:233]
	v_pk_fma_f32 v[234:235], v[18:19], v[240:241], v[234:235]
	v_lshlrev_b32_e32 v236, 16, v78
	v_and_b32_e32 v237, 0xffff0000, v78
	v_pk_fma_f32 v[204:205], v[50:51], v[236:237], v[204:205]
	v_pk_fma_f32 v[206:207], v[48:49], v[236:237], v[206:207]
	v_pk_fma_f32 v[208:209], v[46:47], v[236:237], v[208:209]
	v_pk_fma_f32 v[210:211], v[44:45], v[236:237], v[210:211]
	v_pk_fma_f32 v[212:213], v[42:43], v[236:237], v[212:213]
	v_pk_fma_f32 v[214:215], v[40:41], v[236:237], v[214:215]
	v_pk_fma_f32 v[216:217], v[38:39], v[236:237], v[216:217]
	v_pk_fma_f32 v[218:219], v[36:37], v[236:237], v[218:219]
	v_pk_fma_f32 v[220:221], v[34:35], v[236:237], v[220:221]
	v_pk_fma_f32 v[222:223], v[32:33], v[236:237], v[222:223]
	v_pk_fma_f32 v[224:225], v[30:31], v[236:237], v[224:225]
	v_pk_fma_f32 v[226:227], v[28:29], v[236:237], v[226:227]
	v_pk_fma_f32 v[228:229], v[26:27], v[236:237], v[228:229]
	v_pk_fma_f32 v[230:231], v[24:25], v[236:237], v[230:231]
	v_pk_fma_f32 v[232:233], v[22:23], v[236:237], v[232:233]
	v_pk_fma_f32 v[234:235], v[20:21], v[236:237], v[234:235]
	v_lshlrev_b32_e32 v238, 16, v79
	v_and_b32_e32 v239, 0xffff0000, v79
	v_pk_fma_f32 v[204:205], v[52:53], v[238:239], v[204:205]
	v_pk_fma_f32 v[206:207], v[50:51], v[238:239], v[206:207]
	v_pk_fma_f32 v[208:209], v[48:49], v[238:239], v[208:209]
	v_pk_fma_f32 v[210:211], v[46:47], v[238:239], v[210:211]
	v_pk_fma_f32 v[212:213], v[44:45], v[238:239], v[212:213]
	v_pk_fma_f32 v[214:215], v[42:43], v[238:239], v[214:215]
	v_pk_fma_f32 v[216:217], v[40:41], v[238:239], v[216:217]
	v_pk_fma_f32 v[218:219], v[38:39], v[238:239], v[218:219]
	v_pk_fma_f32 v[220:221], v[36:37], v[238:239], v[220:221]
	v_pk_fma_f32 v[222:223], v[34:35], v[238:239], v[222:223]
	v_pk_fma_f32 v[224:225], v[32:33], v[238:239], v[224:225]
	v_pk_fma_f32 v[226:227], v[30:31], v[238:239], v[226:227]
	v_pk_fma_f32 v[228:229], v[28:29], v[238:239], v[228:229]
	v_pk_fma_f32 v[230:231], v[26:27], v[238:239], v[230:231]
	v_pk_fma_f32 v[232:233], v[24:25], v[238:239], v[232:233]
	v_pk_fma_f32 v[234:235], v[22:23], v[238:239], v[234:235]
	v_lshlrev_b32_e32 v240, 16, v76
	v_and_b32_e32 v241, 0xffff0000, v76
	v_pk_fma_f32 v[204:205], v[54:55], v[240:241], v[204:205]
	v_pk_fma_f32 v[206:207], v[52:53], v[240:241], v[206:207]
	v_pk_fma_f32 v[208:209], v[50:51], v[240:241], v[208:209]
	v_pk_fma_f32 v[210:211], v[48:49], v[240:241], v[210:211]
	v_pk_fma_f32 v[212:213], v[46:47], v[240:241], v[212:213]
	v_pk_fma_f32 v[214:215], v[44:45], v[240:241], v[214:215]
	v_pk_fma_f32 v[216:217], v[42:43], v[240:241], v[216:217]
	v_pk_fma_f32 v[218:219], v[40:41], v[240:241], v[218:219]
	v_pk_fma_f32 v[220:221], v[38:39], v[240:241], v[220:221]
	v_pk_fma_f32 v[222:223], v[36:37], v[240:241], v[222:223]
	v_pk_fma_f32 v[224:225], v[34:35], v[240:241], v[224:225]
	v_pk_fma_f32 v[226:227], v[32:33], v[240:241], v[226:227]
	v_pk_fma_f32 v[228:229], v[30:31], v[240:241], v[228:229]
	v_pk_fma_f32 v[230:231], v[28:29], v[240:241], v[230:231]
	v_pk_fma_f32 v[232:233], v[26:27], v[240:241], v[232:233]
	v_pk_fma_f32 v[234:235], v[24:25], v[240:241], v[234:235]
	v_lshlrev_b32_e32 v236, 16, v77
	v_and_b32_e32 v237, 0xffff0000, v77
	v_pk_fma_f32 v[204:205], v[56:57], v[236:237], v[204:205]
	v_pk_fma_f32 v[206:207], v[54:55], v[236:237], v[206:207]
	v_pk_fma_f32 v[208:209], v[52:53], v[236:237], v[208:209]
	v_pk_fma_f32 v[210:211], v[50:51], v[236:237], v[210:211]
	v_pk_fma_f32 v[212:213], v[48:49], v[236:237], v[212:213]
	v_pk_fma_f32 v[214:215], v[46:47], v[236:237], v[214:215]
	v_pk_fma_f32 v[216:217], v[44:45], v[236:237], v[216:217]
	v_pk_fma_f32 v[218:219], v[42:43], v[236:237], v[218:219]
	v_pk_fma_f32 v[220:221], v[40:41], v[236:237], v[220:221]
	v_pk_fma_f32 v[222:223], v[38:39], v[236:237], v[222:223]
	v_pk_fma_f32 v[224:225], v[36:37], v[236:237], v[224:225]
	v_pk_fma_f32 v[226:227], v[34:35], v[236:237], v[226:227]
	v_pk_fma_f32 v[228:229], v[32:33], v[236:237], v[228:229]
	v_pk_fma_f32 v[230:231], v[30:31], v[236:237], v[230:231]
	v_pk_fma_f32 v[232:233], v[28:29], v[236:237], v[232:233]
	v_pk_fma_f32 v[234:235], v[26:27], v[236:237], v[234:235]
	v_lshlrev_b32_e32 v238, 16, v72
	v_and_b32_e32 v239, 0xffff0000, v72
	v_pk_fma_f32 v[204:205], v[58:59], v[238:239], v[204:205]
	v_pk_fma_f32 v[206:207], v[56:57], v[238:239], v[206:207]
	v_pk_fma_f32 v[208:209], v[54:55], v[238:239], v[208:209]
	v_pk_fma_f32 v[210:211], v[52:53], v[238:239], v[210:211]
	v_pk_fma_f32 v[212:213], v[50:51], v[238:239], v[212:213]
	v_pk_fma_f32 v[214:215], v[48:49], v[238:239], v[214:215]
	v_pk_fma_f32 v[216:217], v[46:47], v[238:239], v[216:217]
; __device__ __forceinline__ void p3_conv(const Ptrs& P, LAS unsigned char* lds, int first, int stride, int tid, int wave, int lane) {
;     ...
;         f32x2 a[16];
; #pragma unroll
;         for (int t = 0; t < 16; ++t) a[t] = cb;
; #pragma unroll
;         for (int r = 0; r < 46; ++r) {
;             const f32x2 u = (f32x2){bflo(uv[r]), bfhi(uv[r])};
; #pragma unroll
;             for (int t = 0; t < 16; ++t) { const int k = r - t; if (k >= 0 && k < CONV_W) a[t] += u * w[k]; }
;         }
	v_pk_fma_f32 v[218:219], v[44:45], v[238:239], v[218:219]
	v_pk_fma_f32 v[220:221], v[42:43], v[238:239], v[220:221]
	v_pk_fma_f32 v[222:223], v[40:41], v[238:239], v[222:223]
	v_pk_fma_f32 v[224:225], v[38:39], v[238:239], v[224:225]
	v_pk_fma_f32 v[226:227], v[36:37], v[238:239], v[226:227]
	v_pk_fma_f32 v[228:229], v[34:35], v[238:239], v[228:229]
	v_pk_fma_f32 v[230:231], v[32:33], v[238:239], v[230:231]
	v_pk_fma_f32 v[232:233], v[30:31], v[238:239], v[232:233]
	v_pk_fma_f32 v[234:235], v[28:29], v[238:239], v[234:235]
	v_lshlrev_b32_e32 v240, 16, v73
	v_and_b32_e32 v241, 0xffff0000, v73
	v_pk_fma_f32 v[204:205], v[60:61], v[240:241], v[204:205]
	v_pk_fma_f32 v[206:207], v[58:59], v[240:241], v[206:207]
	v_pk_fma_f32 v[208:209], v[56:57], v[240:241], v[208:209]
	v_pk_fma_f32 v[210:211], v[54:55], v[240:241], v[210:211]
	v_pk_fma_f32 v[212:213], v[52:53], v[240:241], v[212:213]
	v_pk_fma_f32 v[214:215], v[50:51], v[240:241], v[214:215]
	v_pk_fma_f32 v[216:217], v[48:49], v[240:241], v[216:217]
	v_pk_fma_f32 v[218:219], v[46:47], v[240:241], v[218:219]
	v_pk_fma_f32 v[220:221], v[44:45], v[240:241], v[220:221]
	v_pk_fma_f32 v[222:223], v[42:43], v[240:241], v[222:223]
	v_pk_fma_f32 v[224:225], v[40:41], v[240:241], v[224:225]
	v_pk_fma_f32 v[226:227], v[38:39], v[240:241], v[226:227]
	v_pk_fma_f32 v[228:229], v[36:37], v[240:241], v[228:229]
	v_pk_fma_f32 v[230:231], v[34:35], v[240:241], v[230:231]
	v_pk_fma_f32 v[232:233], v[32:33], v[240:241], v[232:233]
	v_pk_fma_f32 v[234:235], v[30:31], v[240:241], v[234:235]
	v_lshlrev_b32_e32 v236, 16, v74
	v_and_b32_e32 v237, 0xffff0000, v74
	v_pk_fma_f32 v[204:205], v[62:63], v[236:237], v[204:205]
	v_pk_fma_f32 v[206:207], v[60:61], v[236:237], v[206:207]
	v_pk_fma_f32 v[208:209], v[58:59], v[236:237], v[208:209]
	v_pk_fma_f32 v[210:211], v[56:57], v[236:237], v[210:211]
	v_pk_fma_f32 v[212:213], v[54:55], v[236:237], v[212:213]
	v_pk_fma_f32 v[214:215], v[52:53], v[236:237], v[214:215]
	v_pk_fma_f32 v[216:217], v[50:51], v[236:237], v[216:217]
	v_pk_fma_f32 v[218:219], v[48:49], v[236:237], v[218:219]
	v_pk_fma_f32 v[220:221], v[46:47], v[236:237], v[220:221]
	v_pk_fma_f32 v[222:223], v[44:45], v[236:237], v[222:223]
	v_pk_fma_f32 v[224:225], v[42:43], v[236:237], v[224:225]
	v_pk_fma_f32 v[226:227], v[40:41], v[236:237], v[226:227]
	v_pk_fma_f32 v[228:229], v[38:39], v[236:237], v[228:229]
	v_pk_fma_f32 v[230:231], v[36:37], v[236:237], v[230:231]
	v_pk_fma_f32 v[232:233], v[34:35], v[236:237], v[232:233]
	v_pk_fma_f32 v[234:235], v[32:33], v[236:237], v[234:235]
	v_lshlrev_b32_e32 v238, 16, v75
	v_and_b32_e32 v239, 0xffff0000, v75
	v_pk_fma_f32 v[206:207], v[62:63], v[238:239], v[206:207]
	v_pk_fma_f32 v[208:209], v[60:61], v[238:239], v[208:209]
	v_pk_fma_f32 v[210:211], v[58:59], v[238:239], v[210:211]
	v_pk_fma_f32 v[212:213], v[56:57], v[238:239], v[212:213]
	v_pk_fma_f32 v[214:215], v[54:55], v[238:239], v[214:215]
	v_pk_fma_f32 v[216:217], v[52:53], v[238:239], v[216:217]
	v_pk_fma_f32 v[218:219], v[50:51], v[238:239], v[218:219]
	v_pk_fma_f32 v[220:221], v[48:49], v[238:239], v[220:221]
	v_pk_fma_f32 v[222:223], v[46:47], v[238:239], v[222:223]
	v_pk_fma_f32 v[224:225], v[44:45], v[238:239], v[224:225]
	v_pk_fma_f32 v[226:227], v[42:43], v[238:239], v[226:227]
	v_pk_fma_f32 v[228:229], v[40:41], v[238:239], v[228:229]
	v_pk_fma_f32 v[230:231], v[38:39], v[238:239], v[230:231]
	v_pk_fma_f32 v[232:233], v[36:37], v[238:239], v[232:233]
	v_pk_fma_f32 v[234:235], v[34:35], v[238:239], v[234:235]
	v_lshlrev_b32_e32 v240, 16, v136
	v_and_b32_e32 v241, 0xffff0000, v136
	v_pk_fma_f32 v[208:209], v[62:63], v[240:241], v[208:209]
	v_pk_fma_f32 v[210:211], v[60:61], v[240:241], v[210:211]
	v_pk_fma_f32 v[212:213], v[58:59], v[240:241], v[212:213]
	v_pk_fma_f32 v[214:215], v[56:57], v[240:241], v[214:215]
	v_pk_fma_f32 v[216:217], v[54:55], v[240:241], v[216:217]
	v_pk_fma_f32 v[218:219], v[52:53], v[240:241], v[218:219]
	v_pk_fma_f32 v[220:221], v[50:51], v[240:241], v[220:221]
	v_pk_fma_f32 v[222:223], v[48:49], v[240:241], v[222:223]
	v_pk_fma_f32 v[224:225], v[46:47], v[240:241], v[224:225]
	v_pk_fma_f32 v[226:227], v[44:45], v[240:241], v[226:227]
	v_pk_fma_f32 v[228:229], v[42:43], v[240:241], v[228:229]
	v_pk_fma_f32 v[230:231], v[40:41], v[240:241], v[230:231]
	v_pk_fma_f32 v[232:233], v[38:39], v[240:241], v[232:233]
	v_pk_fma_f32 v[234:235], v[36:37], v[240:241], v[234:235]
	v_lshlrev_b32_e32 v236, 16, v142
	v_and_b32_e32 v237, 0xffff0000, v142
	v_pk_fma_f32 v[210:211], v[62:63], v[236:237], v[210:211]
	v_pk_fma_f32 v[212:213], v[60:61], v[236:237], v[212:213]
	v_pk_fma_f32 v[214:215], v[58:59], v[236:237], v[214:215]
	v_pk_fma_f32 v[216:217], v[56:57], v[236:237], v[216:217]
	v_pk_fma_f32 v[218:219], v[54:55], v[236:237], v[218:219]
	v_pk_fma_f32 v[220:221], v[52:53], v[236:237], v[220:221]
	v_pk_fma_f32 v[222:223], v[50:51], v[236:237], v[222:223]
	v_pk_fma_f32 v[224:225], v[48:49], v[236:237], v[224:225]
	v_pk_fma_f32 v[226:227], v[46:47], v[236:237], v[226:227]
	v_pk_fma_f32 v[228:229], v[44:45], v[236:237], v[228:229]
	v_pk_fma_f32 v[230:231], v[42:43], v[236:237], v[230:231]
	v_pk_fma_f32 v[232:233], v[40:41], v[236:237], v[232:233]
	v_pk_fma_f32 v[234:235], v[38:39], v[236:237], v[234:235]
	v_lshlrev_b32_e32 v238, 16, v144
	v_and_b32_e32 v239, 0xffff0000, v144
	v_pk_fma_f32 v[212:213], v[62:63], v[238:239], v[212:213]
	v_pk_fma_f32 v[214:215], v[60:61], v[238:239], v[214:215]
	v_pk_fma_f32 v[216:217], v[58:59], v[238:239], v[216:217]
	v_pk_fma_f32 v[218:219], v[56:57], v[238:239], v[218:219]
	v_pk_fma_f32 v[220:221], v[54:55], v[238:239], v[220:221]
; __device__ __forceinline__ void p3_conv(const Ptrs& P, LAS unsigned char* lds, int first, int stride, int tid, int wave, int lane) {
;     ...
;         for (int r = 0; r < 46; ++r) {
;             const f32x2 u = (f32x2){bflo(uv[r]), bfhi(uv[r])};
; #pragma unroll
;             for (int t = 0; t < 16; ++t) { const int k = r - t; if (k >= 0 && k < CONV_W) a[t] += u * w[k]; }
;         }
; #pragma unroll
;         for (int t = 0; t < 16; ++t) {
;             float s1 = a[t].x + a[t].y, s2 = a[t].x * a[t].x + a[t].y * a[t].y;
	v_pk_fma_f32 v[222:223], v[52:53], v[238:239], v[222:223]
	v_pk_fma_f32 v[224:225], v[50:51], v[238:239], v[224:225]
	v_pk_fma_f32 v[226:227], v[48:49], v[238:239], v[226:227]
	v_pk_fma_f32 v[228:229], v[46:47], v[238:239], v[228:229]
	v_pk_fma_f32 v[230:231], v[44:45], v[238:239], v[230:231]
	v_pk_fma_f32 v[232:233], v[42:43], v[238:239], v[232:233]
	v_pk_fma_f32 v[234:235], v[40:41], v[238:239], v[234:235]
	v_lshlrev_b32_e32 v240, 16, v146
	v_and_b32_e32 v241, 0xffff0000, v146
	v_pk_fma_f32 v[214:215], v[62:63], v[240:241], v[214:215]
	v_pk_fma_f32 v[216:217], v[60:61], v[240:241], v[216:217]
	v_pk_fma_f32 v[218:219], v[58:59], v[240:241], v[218:219]
	v_pk_fma_f32 v[220:221], v[56:57], v[240:241], v[220:221]
	v_pk_fma_f32 v[222:223], v[54:55], v[240:241], v[222:223]
	v_pk_fma_f32 v[224:225], v[52:53], v[240:241], v[224:225]
	v_pk_fma_f32 v[226:227], v[50:51], v[240:241], v[226:227]
	v_pk_fma_f32 v[228:229], v[48:49], v[240:241], v[228:229]
	v_pk_fma_f32 v[230:231], v[46:47], v[240:241], v[230:231]
	v_pk_fma_f32 v[232:233], v[44:45], v[240:241], v[232:233]
	v_pk_fma_f32 v[234:235], v[42:43], v[240:241], v[234:235]
	v_lshlrev_b32_e32 v236, 16, v148
	v_and_b32_e32 v237, 0xffff0000, v148
	v_pk_fma_f32 v[216:217], v[62:63], v[236:237], v[216:217]
	v_pk_fma_f32 v[218:219], v[60:61], v[236:237], v[218:219]
	v_pk_fma_f32 v[220:221], v[58:59], v[236:237], v[220:221]
	v_pk_fma_f32 v[222:223], v[56:57], v[236:237], v[222:223]
	v_pk_fma_f32 v[224:225], v[54:55], v[236:237], v[224:225]
	v_pk_fma_f32 v[226:227], v[52:53], v[236:237], v[226:227]
	v_pk_fma_f32 v[228:229], v[50:51], v[236:237], v[228:229]
	v_pk_fma_f32 v[230:231], v[48:49], v[236:237], v[230:231]
	v_pk_fma_f32 v[232:233], v[46:47], v[236:237], v[232:233]
	v_pk_fma_f32 v[234:235], v[44:45], v[236:237], v[234:235]
	v_lshlrev_b32_e32 v238, 16, v150
	v_and_b32_e32 v239, 0xffff0000, v150
	v_pk_fma_f32 v[218:219], v[62:63], v[238:239], v[218:219]
	v_pk_fma_f32 v[220:221], v[60:61], v[238:239], v[220:221]
	v_pk_fma_f32 v[222:223], v[58:59], v[238:239], v[222:223]
	v_pk_fma_f32 v[224:225], v[56:57], v[238:239], v[224:225]
	v_pk_fma_f32 v[226:227], v[54:55], v[238:239], v[226:227]
	v_pk_fma_f32 v[228:229], v[52:53], v[238:239], v[228:229]
	v_pk_fma_f32 v[230:231], v[50:51], v[238:239], v[230:231]
	v_pk_fma_f32 v[232:233], v[48:49], v[238:239], v[232:233]
	v_pk_fma_f32 v[234:235], v[46:47], v[238:239], v[234:235]
	v_lshlrev_b32_e32 v240, 16, v152
	v_and_b32_e32 v241, 0xffff0000, v152
	v_pk_fma_f32 v[220:221], v[62:63], v[240:241], v[220:221]
	v_pk_fma_f32 v[222:223], v[60:61], v[240:241], v[222:223]
	v_pk_fma_f32 v[224:225], v[58:59], v[240:241], v[224:225]
	v_pk_fma_f32 v[226:227], v[56:57], v[240:241], v[226:227]
	v_pk_fma_f32 v[228:229], v[54:55], v[240:241], v[228:229]
	v_pk_fma_f32 v[230:231], v[52:53], v[240:241], v[230:231]
	v_pk_fma_f32 v[232:233], v[50:51], v[240:241], v[232:233]
	v_pk_fma_f32 v[234:235], v[48:49], v[240:241], v[234:235]
	v_lshlrev_b32_e32 v236, 16, v154
	v_and_b32_e32 v237, 0xffff0000, v154
	v_pk_fma_f32 v[222:223], v[62:63], v[236:237], v[222:223]
	v_pk_fma_f32 v[224:225], v[60:61], v[236:237], v[224:225]
	v_pk_fma_f32 v[226:227], v[58:59], v[236:237], v[226:227]
	v_pk_fma_f32 v[228:229], v[56:57], v[236:237], v[228:229]
	v_pk_fma_f32 v[230:231], v[54:55], v[236:237], v[230:231]
	v_pk_fma_f32 v[232:233], v[52:53], v[236:237], v[232:233]
	v_pk_fma_f32 v[234:235], v[50:51], v[236:237], v[234:235]
	v_lshlrev_b32_e32 v238, 16, v156
	v_and_b32_e32 v239, 0xffff0000, v156
	v_pk_fma_f32 v[224:225], v[62:63], v[238:239], v[224:225]
	v_pk_fma_f32 v[226:227], v[60:61], v[238:239], v[226:227]
	v_pk_fma_f32 v[228:229], v[58:59], v[238:239], v[228:229]
	v_pk_fma_f32 v[230:231], v[56:57], v[238:239], v[230:231]
	v_pk_fma_f32 v[232:233], v[54:55], v[238:239], v[232:233]
	v_pk_fma_f32 v[234:235], v[52:53], v[238:239], v[234:235]
	v_lshlrev_b32_e32 v240, 16, v158
	v_and_b32_e32 v241, 0xffff0000, v158
	v_pk_fma_f32 v[226:227], v[62:63], v[240:241], v[226:227]
	v_pk_fma_f32 v[228:229], v[60:61], v[240:241], v[228:229]
	v_pk_fma_f32 v[230:231], v[58:59], v[240:241], v[230:231]
	v_pk_fma_f32 v[232:233], v[56:57], v[240:241], v[232:233]
	v_pk_fma_f32 v[234:235], v[54:55], v[240:241], v[234:235]
	v_lshlrev_b32_e32 v236, 16, v160
	v_and_b32_e32 v237, 0xffff0000, v160
	v_pk_fma_f32 v[228:229], v[62:63], v[236:237], v[228:229]
	v_pk_fma_f32 v[230:231], v[60:61], v[236:237], v[230:231]
	v_pk_fma_f32 v[232:233], v[58:59], v[236:237], v[232:233]
	v_pk_fma_f32 v[234:235], v[56:57], v[236:237], v[234:235]
	v_lshlrev_b32_e32 v238, 16, v162
	v_and_b32_e32 v239, 0xffff0000, v162
	v_pk_fma_f32 v[230:231], v[62:63], v[238:239], v[230:231]
	v_pk_fma_f32 v[232:233], v[60:61], v[238:239], v[232:233]
	v_pk_fma_f32 v[234:235], v[58:59], v[238:239], v[234:235]
	v_lshlrev_b32_e32 v240, 16, v164
	v_and_b32_e32 v241, 0xffff0000, v164
	v_pk_fma_f32 v[232:233], v[62:63], v[240:241], v[232:233]
	v_pk_fma_f32 v[234:235], v[60:61], v[240:241], v[234:235]
	v_lshlrev_b32_e32 v236, 16, v201
	v_and_b32_e32 v237, 0xffff0000, v201
	v_pk_fma_f32 v[234:235], v[62:63], v[236:237], v[234:235]
	v_pk_mul_f32 v[72:73], v[204:205], v[204:205]
	v_pk_mul_f32 v[74:75], v[206:207], v[206:207]
	v_pk_mul_f32 v[76:77], v[208:209], v[208:209]
	v_pk_mul_f32 v[78:79], v[210:211], v[210:211]
	v_pk_mul_f32 v[80:81], v[212:213], v[212:213]
	v_pk_mul_f32 v[82:83], v[214:215], v[214:215]
	v_pk_mul_f32 v[84:85], v[216:217], v[216:217]
	v_pk_mul_f32 v[86:87], v[218:219], v[218:219]
	v_pk_mul_f32 v[88:89], v[220:221], v[220:221]
	v_pk_mul_f32 v[90:91], v[222:223], v[222:223]
	v_pk_mul_f32 v[92:93], v[224:225], v[224:225]
	v_pk_mul_f32 v[94:95], v[226:227], v[226:227]
; __device__ __forceinline__ void p3_conv(const Ptrs& P, LAS unsigned char* lds, int first, int stride, int tid, int wave, int lane) {
;     ...
;         for (int t = 0; t < 16; ++t) {
;             float s1 = a[t].x + a[t].y, s2 = a[t].x * a[t].x + a[t].y * a[t].y;
; #pragma unroll
;             for (int k = 0; k < 6; ++k) {
;                 s1 += __builtin_bit_cast(float, __builtin_amdgcn_ds_bpermute(bpi[k], __builtin_bit_cast(int, s1)));
;                 s2 += __builtin_bit_cast(float, __builtin_amdgcn_ds_bpermute(bpi[k], __builtin_bit_cast(int, s2)));
	v_pk_mul_f32 v[96:97], v[228:229], v[228:229]
	v_pk_mul_f32 v[98:99], v[230:231], v[230:231]
	v_pk_mul_f32 v[100:101], v[232:233], v[232:233]
	v_pk_mul_f32 v[102:103], v[234:235], v[234:235]
	v_add_f32_e32 v104, v204, v205
	v_add_f32_e32 v106, v206, v207
	v_add_f32_e32 v108, v208, v209
	v_add_f32_e32 v110, v210, v211
	v_add_f32_e32 v112, v212, v213
	v_add_f32_e32 v114, v214, v215
	v_add_f32_e32 v116, v216, v217
	v_add_f32_e32 v118, v218, v219
	v_add_f32_e32 v120, v220, v221
	v_add_f32_e32 v122, v222, v223
	v_add_f32_e32 v124, v224, v225
	v_add_f32_e32 v126, v226, v227
	v_add_f32_e32 v128, v228, v229
	v_add_f32_e32 v130, v230, v231
	v_add_f32_e32 v132, v232, v233
	v_add_f32_e32 v134, v234, v235
	v_add_f32_e32 v105, v72, v73
	v_add_f32_e32 v107, v74, v75
	v_add_f32_e32 v109, v76, v77
	v_add_f32_e32 v111, v78, v79
	v_add_f32_e32 v113, v80, v81
	v_add_f32_e32 v115, v82, v83
	v_add_f32_e32 v117, v84, v85
	v_add_f32_e32 v119, v86, v87
	v_add_f32_e32 v121, v88, v89
	v_add_f32_e32 v123, v90, v91
	v_add_f32_e32 v125, v92, v93
	v_add_f32_e32 v127, v94, v95
	v_add_f32_e32 v129, v96, v97
	v_add_f32_e32 v131, v98, v99
	v_add_f32_e32 v133, v100, v101
	v_add_f32_e32 v135, v102, v103
	v_add_f32_dpp v104, v104, v104 quad_perm:[1,0,3,2] row_mask:0xf bank_mask:0xf
	v_add_f32_dpp v105, v105, v105 quad_perm:[1,0,3,2] row_mask:0xf bank_mask:0xf
	v_add_f32_dpp v106, v106, v106 quad_perm:[1,0,3,2] row_mask:0xf bank_mask:0xf
	v_add_f32_dpp v107, v107, v107 quad_perm:[1,0,3,2] row_mask:0xf bank_mask:0xf
	v_add_f32_dpp v108, v108, v108 quad_perm:[1,0,3,2] row_mask:0xf bank_mask:0xf
	v_add_f32_dpp v109, v109, v109 quad_perm:[1,0,3,2] row_mask:0xf bank_mask:0xf
	v_add_f32_dpp v110, v110, v110 quad_perm:[1,0,3,2] row_mask:0xf bank_mask:0xf
	v_add_f32_dpp v111, v111, v111 quad_perm:[1,0,3,2] row_mask:0xf bank_mask:0xf
	v_add_f32_dpp v112, v112, v112 quad_perm:[1,0,3,2] row_mask:0xf bank_mask:0xf
	v_add_f32_dpp v113, v113, v113 quad_perm:[1,0,3,2] row_mask:0xf bank_mask:0xf
	v_add_f32_dpp v114, v114, v114 quad_perm:[1,0,3,2] row_mask:0xf bank_mask:0xf
	v_add_f32_dpp v115, v115, v115 quad_perm:[1,0,3,2] row_mask:0xf bank_mask:0xf
	v_add_f32_dpp v116, v116, v116 quad_perm:[1,0,3,2] row_mask:0xf bank_mask:0xf
	v_add_f32_dpp v117, v117, v117 quad_perm:[1,0,3,2] row_mask:0xf bank_mask:0xf
	v_add_f32_dpp v118, v118, v118 quad_perm:[1,0,3,2] row_mask:0xf bank_mask:0xf
	v_add_f32_dpp v119, v119, v119 quad_perm:[1,0,3,2] row_mask:0xf bank_mask:0xf
	v_add_f32_dpp v120, v120, v120 quad_perm:[1,0,3,2] row_mask:0xf bank_mask:0xf
	v_add_f32_dpp v121, v121, v121 quad_perm:[1,0,3,2] row_mask:0xf bank_mask:0xf
	v_add_f32_dpp v122, v122, v122 quad_perm:[1,0,3,2] row_mask:0xf bank_mask:0xf
	v_add_f32_dpp v123, v123, v123 quad_perm:[1,0,3,2] row_mask:0xf bank_mask:0xf
	v_add_f32_dpp v124, v124, v124 quad_perm:[1,0,3,2] row_mask:0xf bank_mask:0xf
	v_add_f32_dpp v125, v125, v125 quad_perm:[1,0,3,2] row_mask:0xf bank_mask:0xf
	v_add_f32_dpp v126, v126, v126 quad_perm:[1,0,3,2] row_mask:0xf bank_mask:0xf
	v_add_f32_dpp v127, v127, v127 quad_perm:[1,0,3,2] row_mask:0xf bank_mask:0xf
	v_add_f32_dpp v128, v128, v128 quad_perm:[1,0,3,2] row_mask:0xf bank_mask:0xf
	v_add_f32_dpp v129, v129, v129 quad_perm:[1,0,3,2] row_mask:0xf bank_mask:0xf
	v_add_f32_dpp v130, v130, v130 quad_perm:[1,0,3,2] row_mask:0xf bank_mask:0xf
	v_add_f32_dpp v131, v131, v131 quad_perm:[1,0,3,2] row_mask:0xf bank_mask:0xf
	v_add_f32_dpp v132, v132, v132 quad_perm:[1,0,3,2] row_mask:0xf bank_mask:0xf
	v_add_f32_dpp v133, v133, v133 quad_perm:[1,0,3,2] row_mask:0xf bank_mask:0xf
	v_add_f32_dpp v134, v134, v134 quad_perm:[1,0,3,2] row_mask:0xf bank_mask:0xf
	v_add_f32_dpp v135, v135, v135 quad_perm:[1,0,3,2] row_mask:0xf bank_mask:0xf
	v_add_f32_dpp v104, v104, v104 quad_perm:[2,3,0,1] row_mask:0xf bank_mask:0xf
	v_add_f32_dpp v105, v105, v105 quad_perm:[2,3,0,1] row_mask:0xf bank_mask:0xf
	v_add_f32_dpp v106, v106, v106 quad_perm:[2,3,0,1] row_mask:0xf bank_mask:0xf
	v_add_f32_dpp v107, v107, v107 quad_perm:[2,3,0,1] row_mask:0xf bank_mask:0xf
	v_add_f32_dpp v108, v108, v108 quad_perm:[2,3,0,1] row_mask:0xf bank_mask:0xf
	v_add_f32_dpp v109, v109, v109 quad_perm:[2,3,0,1] row_mask:0xf bank_mask:0xf
	v_add_f32_dpp v110, v110, v110 quad_perm:[2,3,0,1] row_mask:0xf bank_mask:0xf
	v_add_f32_dpp v111, v111, v111 quad_perm:[2,3,0,1] row_mask:0xf bank_mask:0xf
	v_add_f32_dpp v112, v112, v112 quad_perm:[2,3,0,1] row_mask:0xf bank_mask:0xf
	v_add_f32_dpp v113, v113, v113 quad_perm:[2,3,0,1] row_mask:0xf bank_mask:0xf
	v_add_f32_dpp v114, v114, v114 quad_perm:[2,3,0,1] row_mask:0xf bank_mask:0xf
	v_add_f32_dpp v115, v115, v115 quad_perm:[2,3,0,1] row_mask:0xf bank_mask:0xf
	v_add_f32_dpp v116, v116, v116 quad_perm:[2,3,0,1] row_mask:0xf bank_mask:0xf
	v_add_f32_dpp v117, v117, v117 quad_perm:[2,3,0,1] row_mask:0xf bank_mask:0xf
	v_add_f32_dpp v118, v118, v118 quad_perm:[2,3,0,1] row_mask:0xf bank_mask:0xf
	v_add_f32_dpp v119, v119, v119 quad_perm:[2,3,0,1] row_mask:0xf bank_mask:0xf
	v_add_f32_dpp v120, v120, v120 quad_perm:[2,3,0,1] row_mask:0xf bank_mask:0xf
	v_add_f32_dpp v121, v121, v121 quad_perm:[2,3,0,1] row_mask:0xf bank_mask:0xf
	v_add_f32_dpp v122, v122, v122 quad_perm:[2,3,0,1] row_mask:0xf bank_mask:0xf
	v_add_f32_dpp v123, v123, v123 quad_perm:[2,3,0,1] row_mask:0xf bank_mask:0xf
	v_add_f32_dpp v124, v124, v124 quad_perm:[2,3,0,1] row_mask:0xf bank_mask:0xf
	v_add_f32_dpp v125, v125, v125 quad_perm:[2,3,0,1] row_mask:0xf bank_mask:0xf
	v_add_f32_dpp v126, v126, v126 quad_perm:[2,3,0,1] row_mask:0xf bank_mask:0xf
	v_add_f32_dpp v127, v127, v127 quad_perm:[2,3,0,1] row_mask:0xf bank_mask:0xf
; __device__ __forceinline__ void p3_conv(const Ptrs& P, LAS unsigned char* lds, int first, int stride, int tid, int wave, int lane) {
;     ...
;         for (int t = 0; t < 16; ++t) {
;             float s1 = a[t].x + a[t].y, s2 = a[t].x * a[t].x + a[t].y * a[t].y;
; #pragma unroll
;             for (int k = 0; k < 6; ++k) {
;                 s1 += __builtin_bit_cast(float, __builtin_amdgcn_ds_bpermute(bpi[k], __builtin_bit_cast(int, s1)));
;                 s2 += __builtin_bit_cast(float, __builtin_amdgcn_ds_bpermute(bpi[k], __builtin_bit_cast(int, s2)));
;             }
	v_add_f32_dpp v128, v128, v128 quad_perm:[2,3,0,1] row_mask:0xf bank_mask:0xf
	v_add_f32_dpp v129, v129, v129 quad_perm:[2,3,0,1] row_mask:0xf bank_mask:0xf
	v_add_f32_dpp v130, v130, v130 quad_perm:[2,3,0,1] row_mask:0xf bank_mask:0xf
	v_add_f32_dpp v131, v131, v131 quad_perm:[2,3,0,1] row_mask:0xf bank_mask:0xf
	v_add_f32_dpp v132, v132, v132 quad_perm:[2,3,0,1] row_mask:0xf bank_mask:0xf
	v_add_f32_dpp v133, v133, v133 quad_perm:[2,3,0,1] row_mask:0xf bank_mask:0xf
	v_add_f32_dpp v134, v134, v134 quad_perm:[2,3,0,1] row_mask:0xf bank_mask:0xf
	v_add_f32_dpp v135, v135, v135 quad_perm:[2,3,0,1] row_mask:0xf bank_mask:0xf
	v_add_f32_dpp v104, v104, v104 row_half_mirror row_mask:0xf bank_mask:0xf
	v_add_f32_dpp v105, v105, v105 row_half_mirror row_mask:0xf bank_mask:0xf
	v_add_f32_dpp v106, v106, v106 row_half_mirror row_mask:0xf bank_mask:0xf
	v_add_f32_dpp v107, v107, v107 row_half_mirror row_mask:0xf bank_mask:0xf
	v_add_f32_dpp v108, v108, v108 row_half_mirror row_mask:0xf bank_mask:0xf
	v_add_f32_dpp v109, v109, v109 row_half_mirror row_mask:0xf bank_mask:0xf
	v_add_f32_dpp v110, v110, v110 row_half_mirror row_mask:0xf bank_mask:0xf
	v_add_f32_dpp v111, v111, v111 row_half_mirror row_mask:0xf bank_mask:0xf
	v_add_f32_dpp v112, v112, v112 row_half_mirror row_mask:0xf bank_mask:0xf
	v_add_f32_dpp v113, v113, v113 row_half_mirror row_mask:0xf bank_mask:0xf
	v_add_f32_dpp v114, v114, v114 row_half_mirror row_mask:0xf bank_mask:0xf
	v_add_f32_dpp v115, v115, v115 row_half_mirror row_mask:0xf bank_mask:0xf
	v_add_f32_dpp v116, v116, v116 row_half_mirror row_mask:0xf bank_mask:0xf
	v_add_f32_dpp v117, v117, v117 row_half_mirror row_mask:0xf bank_mask:0xf
	v_add_f32_dpp v118, v118, v118 row_half_mirror row_mask:0xf bank_mask:0xf
	v_add_f32_dpp v119, v119, v119 row_half_mirror row_mask:0xf bank_mask:0xf
	v_add_f32_dpp v120, v120, v120 row_half_mirror row_mask:0xf bank_mask:0xf
	v_add_f32_dpp v121, v121, v121 row_half_mirror row_mask:0xf bank_mask:0xf
	v_add_f32_dpp v122, v122, v122 row_half_mirror row_mask:0xf bank_mask:0xf
	v_add_f32_dpp v123, v123, v123 row_half_mirror row_mask:0xf bank_mask:0xf
	v_add_f32_dpp v124, v124, v124 row_half_mirror row_mask:0xf bank_mask:0xf
	v_add_f32_dpp v125, v125, v125 row_half_mirror row_mask:0xf bank_mask:0xf
	v_add_f32_dpp v126, v126, v126 row_half_mirror row_mask:0xf bank_mask:0xf
	v_add_f32_dpp v127, v127, v127 row_half_mirror row_mask:0xf bank_mask:0xf
	v_add_f32_dpp v128, v128, v128 row_half_mirror row_mask:0xf bank_mask:0xf
	v_add_f32_dpp v129, v129, v129 row_half_mirror row_mask:0xf bank_mask:0xf
	v_add_f32_dpp v130, v130, v130 row_half_mirror row_mask:0xf bank_mask:0xf
	v_add_f32_dpp v131, v131, v131 row_half_mirror row_mask:0xf bank_mask:0xf
	v_add_f32_dpp v132, v132, v132 row_half_mirror row_mask:0xf bank_mask:0xf
	v_add_f32_dpp v133, v133, v133 row_half_mirror row_mask:0xf bank_mask:0xf
	v_add_f32_dpp v134, v134, v134 row_half_mirror row_mask:0xf bank_mask:0xf
	v_add_f32_dpp v135, v135, v135 row_half_mirror row_mask:0xf bank_mask:0xf
	v_add_f32_dpp v104, v104, v104 row_mirror row_mask:0xf bank_mask:0xf
	v_add_f32_dpp v105, v105, v105 row_mirror row_mask:0xf bank_mask:0xf
	v_add_f32_dpp v106, v106, v106 row_mirror row_mask:0xf bank_mask:0xf
	v_add_f32_dpp v107, v107, v107 row_mirror row_mask:0xf bank_mask:0xf
	v_add_f32_dpp v108, v108, v108 row_mirror row_mask:0xf bank_mask:0xf
	v_add_f32_dpp v109, v109, v109 row_mirror row_mask:0xf bank_mask:0xf
	v_add_f32_dpp v110, v110, v110 row_mirror row_mask:0xf bank_mask:0xf
	v_add_f32_dpp v111, v111, v111 row_mirror row_mask:0xf bank_mask:0xf
	v_add_f32_dpp v112, v112, v112 row_mirror row_mask:0xf bank_mask:0xf
	v_add_f32_dpp v113, v113, v113 row_mirror row_mask:0xf bank_mask:0xf
	v_add_f32_dpp v114, v114, v114 row_mirror row_mask:0xf bank_mask:0xf
	v_add_f32_dpp v115, v115, v115 row_mirror row_mask:0xf bank_mask:0xf
	v_add_f32_dpp v116, v116, v116 row_mirror row_mask:0xf bank_mask:0xf
	v_add_f32_dpp v117, v117, v117 row_mirror row_mask:0xf bank_mask:0xf
	v_add_f32_dpp v118, v118, v118 row_mirror row_mask:0xf bank_mask:0xf
	v_add_f32_dpp v119, v119, v119 row_mirror row_mask:0xf bank_mask:0xf
	v_add_f32_dpp v120, v120, v120 row_mirror row_mask:0xf bank_mask:0xf
	v_add_f32_dpp v121, v121, v121 row_mirror row_mask:0xf bank_mask:0xf
	v_add_f32_dpp v122, v122, v122 row_mirror row_mask:0xf bank_mask:0xf
	v_add_f32_dpp v123, v123, v123 row_mirror row_mask:0xf bank_mask:0xf
	v_add_f32_dpp v124, v124, v124 row_mirror row_mask:0xf bank_mask:0xf
	v_add_f32_dpp v125, v125, v125 row_mirror row_mask:0xf bank_mask:0xf
	v_add_f32_dpp v126, v126, v126 row_mirror row_mask:0xf bank_mask:0xf
	v_add_f32_dpp v127, v127, v127 row_mirror row_mask:0xf bank_mask:0xf
	v_add_f32_dpp v128, v128, v128 row_mirror row_mask:0xf bank_mask:0xf
	v_add_f32_dpp v129, v129, v129 row_mirror row_mask:0xf bank_mask:0xf
	v_add_f32_dpp v130, v130, v130 row_mirror row_mask:0xf bank_mask:0xf
	v_add_f32_dpp v131, v131, v131 row_mirror row_mask:0xf bank_mask:0xf
	v_add_f32_dpp v132, v132, v132 row_mirror row_mask:0xf bank_mask:0xf
	v_add_f32_dpp v133, v133, v133 row_mirror row_mask:0xf bank_mask:0xf
; __device__ __forceinline__ void p3_conv(const Ptrs& P, LAS unsigned char* lds, int first, int stride, int tid, int wave, int lane) {
;     ...
; #pragma unroll
;             for (int k = 0; k < 6; ++k) {
;                 s1 += __builtin_bit_cast(float, __builtin_amdgcn_ds_bpermute(bpi[k], __builtin_bit_cast(int, s1)));
;                 s2 += __builtin_bit_cast(float, __builtin_amdgcn_ds_bpermute(bpi[k], __builtin_bit_cast(int, s2)));
;             }
;             if (lane == 0) { red[(wave * 16 + t) * 2] = s1; red[(wave * 16 + t) * 2 + 1] = s2; }
;         }
	v_add_f32_dpp v134, v134, v134 row_mirror row_mask:0xf bank_mask:0xf
	v_add_f32_dpp v135, v135, v135 row_mirror row_mask:0xf bank_mask:0xf
	v_add_f32_dpp v104, v104, v104 row_bcast:15 row_mask:0xa bank_mask:0xf
	v_add_f32_dpp v105, v105, v105 row_bcast:15 row_mask:0xa bank_mask:0xf
	v_add_f32_dpp v106, v106, v106 row_bcast:15 row_mask:0xa bank_mask:0xf
	v_add_f32_dpp v107, v107, v107 row_bcast:15 row_mask:0xa bank_mask:0xf
	v_add_f32_dpp v108, v108, v108 row_bcast:15 row_mask:0xa bank_mask:0xf
	v_add_f32_dpp v109, v109, v109 row_bcast:15 row_mask:0xa bank_mask:0xf
	v_add_f32_dpp v110, v110, v110 row_bcast:15 row_mask:0xa bank_mask:0xf
	v_add_f32_dpp v111, v111, v111 row_bcast:15 row_mask:0xa bank_mask:0xf
	v_add_f32_dpp v112, v112, v112 row_bcast:15 row_mask:0xa bank_mask:0xf
	v_add_f32_dpp v113, v113, v113 row_bcast:15 row_mask:0xa bank_mask:0xf
	v_add_f32_dpp v114, v114, v114 row_bcast:15 row_mask:0xa bank_mask:0xf
	v_add_f32_dpp v115, v115, v115 row_bcast:15 row_mask:0xa bank_mask:0xf
	v_add_f32_dpp v116, v116, v116 row_bcast:15 row_mask:0xa bank_mask:0xf
	v_add_f32_dpp v117, v117, v117 row_bcast:15 row_mask:0xa bank_mask:0xf
	v_add_f32_dpp v118, v118, v118 row_bcast:15 row_mask:0xa bank_mask:0xf
	v_add_f32_dpp v119, v119, v119 row_bcast:15 row_mask:0xa bank_mask:0xf
	v_add_f32_dpp v120, v120, v120 row_bcast:15 row_mask:0xa bank_mask:0xf
	v_add_f32_dpp v121, v121, v121 row_bcast:15 row_mask:0xa bank_mask:0xf
	v_add_f32_dpp v122, v122, v122 row_bcast:15 row_mask:0xa bank_mask:0xf
	v_add_f32_dpp v123, v123, v123 row_bcast:15 row_mask:0xa bank_mask:0xf
	v_add_f32_dpp v124, v124, v124 row_bcast:15 row_mask:0xa bank_mask:0xf
	v_add_f32_dpp v125, v125, v125 row_bcast:15 row_mask:0xa bank_mask:0xf
	v_add_f32_dpp v126, v126, v126 row_bcast:15 row_mask:0xa bank_mask:0xf
	v_add_f32_dpp v127, v127, v127 row_bcast:15 row_mask:0xa bank_mask:0xf
	v_add_f32_dpp v128, v128, v128 row_bcast:15 row_mask:0xa bank_mask:0xf
	v_add_f32_dpp v129, v129, v129 row_bcast:15 row_mask:0xa bank_mask:0xf
	v_add_f32_dpp v130, v130, v130 row_bcast:15 row_mask:0xa bank_mask:0xf
	v_add_f32_dpp v131, v131, v131 row_bcast:15 row_mask:0xa bank_mask:0xf
	v_add_f32_dpp v132, v132, v132 row_bcast:15 row_mask:0xa bank_mask:0xf
	v_add_f32_dpp v133, v133, v133 row_bcast:15 row_mask:0xa bank_mask:0xf
	v_add_f32_dpp v134, v134, v134 row_bcast:15 row_mask:0xa bank_mask:0xf
	v_add_f32_dpp v135, v135, v135 row_bcast:15 row_mask:0xa bank_mask:0xf
	v_add_f32_dpp v104, v104, v104 row_bcast:31 row_mask:0xc bank_mask:0xf
	v_add_f32_dpp v105, v105, v105 row_bcast:31 row_mask:0xc bank_mask:0xf
	v_add_f32_dpp v106, v106, v106 row_bcast:31 row_mask:0xc bank_mask:0xf
	v_add_f32_dpp v107, v107, v107 row_bcast:31 row_mask:0xc bank_mask:0xf
	v_add_f32_dpp v108, v108, v108 row_bcast:31 row_mask:0xc bank_mask:0xf
	v_add_f32_dpp v109, v109, v109 row_bcast:31 row_mask:0xc bank_mask:0xf
	v_add_f32_dpp v110, v110, v110 row_bcast:31 row_mask:0xc bank_mask:0xf
	v_add_f32_dpp v111, v111, v111 row_bcast:31 row_mask:0xc bank_mask:0xf
	v_add_f32_dpp v112, v112, v112 row_bcast:31 row_mask:0xc bank_mask:0xf
	v_add_f32_dpp v113, v113, v113 row_bcast:31 row_mask:0xc bank_mask:0xf
	v_add_f32_dpp v114, v114, v114 row_bcast:31 row_mask:0xc bank_mask:0xf
	v_add_f32_dpp v115, v115, v115 row_bcast:31 row_mask:0xc bank_mask:0xf
	v_add_f32_dpp v116, v116, v116 row_bcast:31 row_mask:0xc bank_mask:0xf
	v_add_f32_dpp v117, v117, v117 row_bcast:31 row_mask:0xc bank_mask:0xf
	v_add_f32_dpp v118, v118, v118 row_bcast:31 row_mask:0xc bank_mask:0xf
	v_add_f32_dpp v119, v119, v119 row_bcast:31 row_mask:0xc bank_mask:0xf
	v_add_f32_dpp v120, v120, v120 row_bcast:31 row_mask:0xc bank_mask:0xf
	v_add_f32_dpp v121, v121, v121 row_bcast:31 row_mask:0xc bank_mask:0xf
	v_add_f32_dpp v122, v122, v122 row_bcast:31 row_mask:0xc bank_mask:0xf
	v_add_f32_dpp v123, v123, v123 row_bcast:31 row_mask:0xc bank_mask:0xf
	v_add_f32_dpp v124, v124, v124 row_bcast:31 row_mask:0xc bank_mask:0xf
	v_add_f32_dpp v125, v125, v125 row_bcast:31 row_mask:0xc bank_mask:0xf
	v_add_f32_dpp v126, v126, v126 row_bcast:31 row_mask:0xc bank_mask:0xf
	v_add_f32_dpp v127, v127, v127 row_bcast:31 row_mask:0xc bank_mask:0xf
	v_add_f32_dpp v128, v128, v128 row_bcast:31 row_mask:0xc bank_mask:0xf
	v_add_f32_dpp v129, v129, v129 row_bcast:31 row_mask:0xc bank_mask:0xf
	v_add_f32_dpp v130, v130, v130 row_bcast:31 row_mask:0xc bank_mask:0xf
	v_add_f32_dpp v131, v131, v131 row_bcast:31 row_mask:0xc bank_mask:0xf
	v_add_f32_dpp v132, v132, v132 row_bcast:31 row_mask:0xc bank_mask:0xf
	v_add_f32_dpp v133, v133, v133 row_bcast:31 row_mask:0xc bank_mask:0xf
	v_add_f32_dpp v134, v134, v134 row_bcast:31 row_mask:0xc bank_mask:0xf
	v_add_f32_dpp v135, v135, v135 row_bcast:31 row_mask:0xc bank_mask:0xf
	v_mov_b32_e32 v242, s37
	s_mov_b64 s[0:1], exec
	s_mov_b32 exec_lo, 0
	s_mov_b32 exec_hi, 0x80000000
	ds_write_b128 v242, v[104:107]
	ds_write_b128 v242, v[108:111] offset:16
	ds_write_b128 v242, v[112:115] offset:32
	ds_write_b128 v242, v[116:119] offset:48
	ds_write_b128 v242, v[120:123] offset:64
	ds_write_b128 v242, v[124:127] offset:80
	ds_write_b128 v242, v[128:131] offset:96
	ds_write_b128 v242, v[132:135] offset:112
	s_mov_b64 exec, s[0:1]
